# v15 + packed f32 mul/fma in GEMM epilogues split into scalar pairs
# baseline (speedup 1.0000x reference)
.LBB0_427:
	s_waitcnt vmcnt(0)
	v_mul_f32_e32 v126, v126, v152
	v_mul_f32_e32 v127, v127, v152
	v_lshlrev_b64 v[158:159], 7, v[146:147]
	v_mul_f32_e32 v147, 0xbfb8aa3b, v126
	v_exp_f32_e32 v147, v147
	v_mul_f32_e32 v157, 0xbfb8aa3b, v127
	v_exp_f32_e32 v157, v157
	v_mul_f32_e32 v160, v116, v152
	v_mul_f32_e32 v161, v117, v152
	v_add_f32_e32 v116, 1.0, v147
	v_rcp_f32_e32 v147, v116
	v_add_f32_e32 v116, 1.0, v157
	v_mul_f32_e32 v128, v128, v152
	v_mul_f32_e32 v129, v129, v152
	v_mul_f32_e32 v118, v118, v152
	v_mul_f32_e32 v119, v119, v152
	v_rcp_f32_e32 v157, v116
	v_mul_f32_e32 v116, v114, v152
	v_mul_f32_e32 v117, v115, v152
	v_mul_f32_e32 v114, v126, v147
	v_mul_f32_e32 v114, v118, v114
	v_mul_f32_e32 v118, 0xbfb8aa3b, v128
	v_mul_f32_e32 v126, 0xbfb8aa3b, v129
	v_exp_f32_e32 v118, v118
	v_exp_f32_e32 v126, v126
	v_mul_f32_e32 v115, v127, v157
	v_mul_f32_e32 v115, v119, v115
	v_add_f32_e32 v118, 1.0, v118
	v_add_f32_e32 v119, 1.0, v126
	v_rcp_f32_e32 v118, v118
	v_rcp_f32_e32 v119, v119
	v_mul_f32_e32 v122, v122, v152
	v_mul_f32_e32 v123, v123, v152
	v_mul_f32_e32 v120, v120, v152
	v_mul_f32_e32 v121, v121, v152
	v_cvt_pk_bf16_f32 v114, v114, v115
	v_mul_f32_e32 v115, v128, v118
	v_mul_f32_e32 v118, v129, v119
	v_mul_f32_e32 v119, 0xbfb8aa3b, v122
	v_mul_f32_e32 v115, v120, v115
	v_exp_f32_e32 v119, v119
	v_mul_f32_e32 v120, 0xbfb8aa3b, v123
	v_exp_f32_e32 v120, v120
	v_mul_f32_e32 v124, v124, v152
	v_mul_f32_e32 v125, v125, v152
	v_add_f32_e32 v119, 1.0, v119
	v_rcp_f32_e32 v119, v119
	v_add_f32_e32 v120, 1.0, v120
	v_rcp_f32_e32 v120, v120
	v_mul_f32_e32 v118, v121, v118
	v_cvt_pk_bf16_f32 v115, v115, v118
	v_mul_f32_e32 v118, v122, v119
	v_mul_f32_e32 v119, 0xbfb8aa3b, v124
	v_mul_f32_e32 v116, v116, v118
	v_mul_f32_e32 v118, v123, v120
	v_exp_f32_e32 v119, v119
	v_mul_f32_e32 v120, 0xbfb8aa3b, v125
	v_exp_f32_e32 v120, v120
	s_lshl_b32 s19, s26, 7
	s_or_b32 s19, s19, s43
	s_ashr_i32 s28, s19, 6
	v_mul_f32_e32 v117, v117, v118
	v_add_f32_e32 v118, 1.0, v119
	v_lshrrev_b32_e32 v148, 1, v148
	s_ashr_i32 s29, s28, 31
	v_rcp_f32_e32 v118, v118
	v_add_f32_e32 v119, 1.0, v120
	s_lshl_b64 s[28:29], s[28:29], 19
	v_and_or_b32 v148, v148, 24, s46
	v_rcp_f32_e32 v119, v119
	v_or_b32_e32 v148, s28, v148
	v_mov_b32_e32 v149, s29
	v_readlane_b32 s28, v245, 14
	v_readlane_b32 s29, v245, 15
	v_cvt_pk_bf16_f32 v116, v116, v117
	v_mul_f32_e32 v117, v124, v118
	v_mul_f32_e32 v117, v160, v117
	v_lshl_add_u64 v[158:159], s[28:29], 0, v[158:159]
	v_lshl_add_u64 v[158:159], v[148:149], 1, v[158:159]
	v_mul_f32_e32 v118, v125, v119
	v_mul_f32_e32 v118, v161, v118
	v_cvt_pk_bf16_f32 v117, v117, v118
	global_store_dwordx4 v[158:159], v[114:117], off
	s_and_b64 vcc, exec, s[8:9]
	s_nop 0
	v_or_b32_e32 v114, 16, v146
	v_ashrrev_i32_e32 v115, 31, v114
	s_cbranch_vccnz .LBB0_429
	v_readlane_b32 s28, v245, 16
	v_readlane_b32 s29, v245, 17
	s_nop 1
	v_lshl_add_u64 v[116:117], v[114:115], 2, s[28:29]
	global_load_dword v150, v[116:117], off
.LBB0_429:
	s_waitcnt vmcnt(0)
	v_mul_f32_e32 v110, v110, v150
	v_mul_f32_e32 v111, v111, v150
	v_mul_f32_e32 v116, v100, v150
	v_mul_f32_e32 v117, v101, v150
	v_mul_f32_e32 v100, 0xbfb8aa3b, v110
	v_exp_f32_e32 v100, v100
	v_mul_f32_e32 v118, v98, v150
	v_mul_f32_e32 v119, v99, v150
	v_mul_f32_e32 v101, 0xbfb8aa3b, v111
	v_exp_f32_e32 v101, v101
	v_add_f32_e32 v98, 1.0, v100
	v_rcp_f32_e32 v99, v98
	v_mul_f32_e32 v112, v112, v150
	v_mul_f32_e32 v113, v113, v150
	v_mul_f32_e32 v102, v102, v150
	v_mul_f32_e32 v103, v103, v150
	v_add_f32_e32 v98, 1.0, v101
	v_mul_f32_e32 v99, v110, v99
	v_mul_f32_e32 v99, v102, v99
	v_mul_f32_e32 v101, 0xbfb8aa3b, v112
	v_mul_f32_e32 v102, 0xbfb8aa3b, v113
	v_exp_f32_e32 v101, v101
	v_exp_f32_e32 v102, v102
	v_rcp_f32_e32 v100, v98
	v_mul_f32_e32 v106, v106, v150
	v_mul_f32_e32 v107, v107, v150
	v_add_f32_e32 v101, 1.0, v101
	v_add_f32_e32 v102, 1.0, v102
	v_rcp_f32_e32 v101, v101
	v_rcp_f32_e32 v102, v102
	v_mul_f32_e32 v100, v111, v100
	v_mul_f32_e32 v100, v103, v100
	v_cvt_pk_bf16_f32 v100, v99, v100
	v_mul_f32_e32 v99, v112, v101
	v_mul_f32_e32 v101, v113, v102
	v_mul_f32_e32 v102, 0xbfb8aa3b, v106
	v_mul_f32_e32 v103, 0xbfb8aa3b, v107
	v_exp_f32_e32 v102, v102
	v_exp_f32_e32 v103, v103
	v_mul_f32_e32 v104, v104, v150
	v_mul_f32_e32 v105, v105, v150
	v_mul_f32_e32 v108, v108, v150
	v_mul_f32_e32 v109, v109, v150
	v_add_f32_e32 v102, 1.0, v102
	v_add_f32_e32 v103, 1.0, v103
	v_rcp_f32_e32 v102, v102
	v_rcp_f32_e32 v103, v103
	v_mul_f32_e32 v99, v104, v99
	v_mul_f32_e32 v101, v105, v101
	v_cvt_pk_bf16_f32 v101, v99, v101
	v_mul_f32_e32 v99, v106, v102
	v_mul_f32_e32 v102, v107, v103
	v_mul_f32_e32 v103, 0xbfb8aa3b, v108
	v_mul_f32_e32 v104, 0xbfb8aa3b, v109
	v_exp_f32_e32 v103, v103
	v_exp_f32_e32 v104, v104
	v_readlane_b32 s28, v245, 14
	v_lshlrev_b64 v[114:115], 7, v[114:115]
	v_add_f32_e32 v103, 1.0, v103
	v_add_f32_e32 v104, 1.0, v104
	v_rcp_f32_e32 v103, v103
	v_rcp_f32_e32 v104, v104
	v_readlane_b32 s29, v245, 15
	v_mul_f32_e32 v99, v118, v99
	v_mul_f32_e32 v102, v119, v102
	v_lshl_add_u64 v[114:115], s[28:29], 0, v[114:115]
	v_cvt_pk_bf16_f32 v102, v99, v102
	v_mul_f32_e32 v99, v108, v103
	v_mul_f32_e32 v103, v109, v104
	v_lshl_add_u64 v[114:115], v[148:149], 1, v[114:115]
	v_mul_f32_e32 v103, v117, v103
	v_mul_f32_e32 v99, v116, v99
	v_cvt_pk_bf16_f32 v103, v99, v103
	global_store_dwordx4 v[114:115], v[100:103], off
	v_mov_b32_e32 v98, 1.0
	s_and_b64 vcc, exec, s[8:9]
	v_or_b32_e32 v102, 32, v146
	v_ashrrev_i32_e32 v103, 31, v102
	v_mov_b32_e32 v100, 1.0
	s_cbranch_vccnz .LBB0_431
	v_readlane_b32 s28, v245, 16
	v_readlane_b32 s29, v245, 17
	s_nop 1
	v_lshl_add_u64 v[100:101], v[102:103], 2, s[28:29]
	global_load_dword v100, v[100:101], off
.LBB0_431:
	s_waitcnt vmcnt(0)
	v_mul_f32_e32 v94, v94, v100
	v_mul_f32_e32 v95, v95, v100
	v_mul_f32_e32 v96, v96, v100
	v_mul_f32_e32 v97, v97, v100
	v_mul_f32_e32 v92, v92, v100
	v_mul_f32_e32 v93, v93, v100
	v_mul_f32_e32 v90, v90, v100
	v_mul_f32_e32 v91, v91, v100
	v_mul_f32_e32 v88, v88, v100
	v_mul_f32_e32 v89, v89, v100
	v_mul_f32_e32 v86, v86, v100
	v_mul_f32_e32 v87, v87, v100
	v_mul_f32_e32 v99, 0xbfb8aa3b, v94
	v_mul_f32_e32 v101, 0xbfb8aa3b, v95
	v_exp_f32_e32 v99, v99
	v_exp_f32_e32 v101, v101
	v_readlane_b32 s28, v245, 14
	v_lshlrev_b64 v[102:103], 7, v[102:103]
	v_readlane_b32 s29, v245, 15
	v_mul_f32_e32 v104, v84, v100
	v_mul_f32_e32 v105, v85, v100
	v_add_f32_e32 v84, 1.0, v99
	v_rcp_f32_e32 v99, v84
	v_add_f32_e32 v84, 1.0, v101
	v_rcp_f32_e32 v101, v84
	v_lshl_add_u64 v[102:103], s[28:29], 0, v[102:103]
	v_lshl_add_u64 v[102:103], v[148:149], 1, v[102:103]
	s_and_b64 vcc, exec, s[8:9]
	v_mul_f32_e32 v84, v82, v100
	v_mul_f32_e32 v85, v83, v100
	v_mul_f32_e32 v82, v94, v99
	v_mul_f32_e32 v82, v86, v82
	v_mul_f32_e32 v86, 0xbfb8aa3b, v96
	v_mul_f32_e32 v94, 0xbfb8aa3b, v97
	v_exp_f32_e32 v86, v86
	v_exp_f32_e32 v94, v94
	v_mul_f32_e32 v83, v95, v101
	v_mul_f32_e32 v83, v87, v83
	v_add_f32_e32 v86, 1.0, v86
	v_add_f32_e32 v87, 1.0, v94
	v_rcp_f32_e32 v86, v86
	v_rcp_f32_e32 v87, v87
	v_cvt_pk_bf16_f32 v82, v82, v83
	v_mul_f32_e32 v83, v96, v86
	v_mul_f32_e32 v86, v97, v87
	v_mul_f32_e32 v87, 0xbfb8aa3b, v90
	v_mul_f32_e32 v83, v88, v83
	v_exp_f32_e32 v87, v87
	v_mul_f32_e32 v88, 0xbfb8aa3b, v91
	v_exp_f32_e32 v88, v88
	v_mul_f32_e32 v86, v89, v86
	v_add_f32_e32 v87, 1.0, v87
	v_rcp_f32_e32 v87, v87
	v_add_f32_e32 v88, 1.0, v88
	v_rcp_f32_e32 v88, v88
	v_cvt_pk_bf16_f32 v83, v83, v86
	v_mul_f32_e32 v86, v90, v87
	v_mul_f32_e32 v87, 0xbfb8aa3b, v92
	v_mul_f32_e32 v84, v84, v86
	v_mul_f32_e32 v86, v91, v88
	v_exp_f32_e32 v87, v87
	v_mul_f32_e32 v88, 0xbfb8aa3b, v93
	v_exp_f32_e32 v88, v88
	v_mul_f32_e32 v85, v85, v86
	v_add_f32_e32 v86, 1.0, v87
	v_rcp_f32_e32 v86, v86
	v_add_f32_e32 v87, 1.0, v88
	v_rcp_f32_e32 v87, v87
	v_cvt_pk_bf16_f32 v84, v84, v85
	v_mul_f32_e32 v85, v92, v86
	v_mul_f32_e32 v85, v104, v85
	v_mul_f32_e32 v86, v93, v87
	v_mul_f32_e32 v86, v105, v86
	v_cvt_pk_bf16_f32 v85, v85, v86
	global_store_dwordx4 v[102:103], v[82:85], off
	s_nop 1
	v_or_b32_e32 v82, 48, v146
	v_ashrrev_i32_e32 v83, 31, v82
	s_cbranch_vccnz .LBB0_433
	v_readlane_b32 s28, v245, 16
	v_readlane_b32 s29, v245, 17
	s_nop 1
	v_lshl_add_u64 v[84:85], v[82:83], 2, s[28:29]
	global_load_dword v98, v[84:85], off
.LBB0_433:
	s_waitcnt vmcnt(0)
	v_mul_f32_e32 v78, v78, v98
	v_mul_f32_e32 v79, v79, v98
	v_mul_f32_e32 v84, v68, v98
	v_mul_f32_e32 v85, v69, v98
	v_mul_f32_e32 v68, 0xbfb8aa3b, v78
	v_exp_f32_e32 v68, v68
	v_mul_f32_e32 v86, v66, v98
	v_mul_f32_e32 v87, v67, v98
	v_mul_f32_e32 v69, 0xbfb8aa3b, v79
	v_exp_f32_e32 v69, v69
	v_add_f32_e32 v66, 1.0, v68
	v_rcp_f32_e32 v67, v66
	v_mul_f32_e32 v80, v80, v98
	v_mul_f32_e32 v81, v81, v98
	v_mul_f32_e32 v70, v70, v98
	v_mul_f32_e32 v71, v71, v98
	v_add_f32_e32 v66, 1.0, v69
	v_mul_f32_e32 v67, v78, v67
	v_mul_f32_e32 v67, v70, v67
	v_mul_f32_e32 v69, 0xbfb8aa3b, v80
	v_mul_f32_e32 v70, 0xbfb8aa3b, v81
	v_exp_f32_e32 v69, v69
	v_exp_f32_e32 v70, v70
	v_rcp_f32_e32 v68, v66
	v_mul_f32_e32 v74, v74, v98
	v_mul_f32_e32 v75, v75, v98
	v_add_f32_e32 v69, 1.0, v69
	v_add_f32_e32 v70, 1.0, v70
	v_rcp_f32_e32 v69, v69
	v_rcp_f32_e32 v70, v70
	v_mul_f32_e32 v68, v79, v68
	v_mul_f32_e32 v68, v71, v68
	v_cvt_pk_bf16_f32 v68, v67, v68
	v_mul_f32_e32 v67, v80, v69
	v_mul_f32_e32 v69, v81, v70
	v_mul_f32_e32 v70, 0xbfb8aa3b, v74
	v_mul_f32_e32 v71, 0xbfb8aa3b, v75
	v_exp_f32_e32 v70, v70
	v_exp_f32_e32 v71, v71
	v_mul_f32_e32 v72, v72, v98
	v_mul_f32_e32 v73, v73, v98
	v_mul_f32_e32 v76, v76, v98
	v_mul_f32_e32 v77, v77, v98
	v_add_f32_e32 v70, 1.0, v70
	v_add_f32_e32 v71, 1.0, v71
	v_rcp_f32_e32 v70, v70
	v_rcp_f32_e32 v71, v71
	v_mul_f32_e32 v67, v72, v67
	v_mul_f32_e32 v69, v73, v69
	v_cvt_pk_bf16_f32 v69, v67, v69
	v_mul_f32_e32 v67, v74, v70
	v_mul_f32_e32 v70, v75, v71
	v_mul_f32_e32 v71, 0xbfb8aa3b, v76
	v_mul_f32_e32 v72, 0xbfb8aa3b, v77
	v_exp_f32_e32 v71, v71
	v_exp_f32_e32 v72, v72
	v_readlane_b32 s28, v245, 14
	v_lshlrev_b64 v[82:83], 7, v[82:83]
	v_add_f32_e32 v71, 1.0, v71
	v_add_f32_e32 v72, 1.0, v72
	v_rcp_f32_e32 v71, v71
	v_rcp_f32_e32 v72, v72
	v_readlane_b32 s29, v245, 15
	v_mul_f32_e32 v67, v86, v67
	v_mul_f32_e32 v70, v87, v70
	v_lshl_add_u64 v[82:83], s[28:29], 0, v[82:83]
	v_cvt_pk_bf16_f32 v70, v67, v70
	v_mul_f32_e32 v67, v76, v71
	v_mul_f32_e32 v71, v77, v72
	v_lshl_add_u64 v[82:83], v[148:149], 1, v[82:83]
	v_mul_f32_e32 v71, v85, v71
	v_mul_f32_e32 v67, v84, v67
	v_cvt_pk_bf16_f32 v71, v67, v71
	global_store_dwordx4 v[82:83], v[68:71], off
	v_mov_b32_e32 v66, 1.0
	s_and_b64 vcc, exec, s[8:9]
	v_add_u32_e32 v70, 0x80, v146
	v_ashrrev_i32_e32 v71, 31, v70
	v_mov_b32_e32 v68, 1.0
	s_cbranch_vccnz .LBB0_435
	v_readlane_b32 s28, v245, 16
	v_readlane_b32 s29, v245, 17
	s_nop 1
	v_lshl_add_u64 v[68:69], v[70:71], 2, s[28:29]
	global_load_dword v68, v[68:69], off
.LBB0_435:
	s_waitcnt vmcnt(0)
	v_mul_f32_e32 v62, v62, v68
	v_mul_f32_e32 v63, v63, v68
	v_mul_f32_e32 v64, v64, v68
	v_mul_f32_e32 v65, v65, v68
	v_mul_f32_e32 v60, v60, v68
	v_mul_f32_e32 v61, v61, v68
	v_mul_f32_e32 v58, v58, v68
	v_mul_f32_e32 v59, v59, v68
	v_mul_f32_e32 v56, v56, v68
	v_mul_f32_e32 v57, v57, v68
	v_mul_f32_e32 v54, v54, v68
	v_mul_f32_e32 v55, v55, v68
	v_mul_f32_e32 v67, 0xbfb8aa3b, v62
	v_mul_f32_e32 v69, 0xbfb8aa3b, v63
	v_exp_f32_e32 v67, v67
	v_exp_f32_e32 v69, v69
	v_readlane_b32 s28, v245, 14
	v_lshlrev_b64 v[70:71], 7, v[70:71]
	v_readlane_b32 s29, v245, 15
	v_mul_f32_e32 v72, v52, v68
	v_mul_f32_e32 v73, v53, v68
	v_add_f32_e32 v52, 1.0, v67
	v_rcp_f32_e32 v67, v52
	v_add_f32_e32 v52, 1.0, v69
	v_rcp_f32_e32 v69, v52
	v_lshl_add_u64 v[70:71], s[28:29], 0, v[70:71]
	v_lshl_add_u64 v[70:71], v[148:149], 1, v[70:71]
	s_and_b64 vcc, exec, s[8:9]
	v_mul_f32_e32 v52, v50, v68
	v_mul_f32_e32 v53, v51, v68
	v_mul_f32_e32 v50, v62, v67
	v_mul_f32_e32 v50, v54, v50
	v_mul_f32_e32 v54, 0xbfb8aa3b, v64
	v_mul_f32_e32 v62, 0xbfb8aa3b, v65
	v_exp_f32_e32 v54, v54
	v_exp_f32_e32 v62, v62
	v_mul_f32_e32 v51, v63, v69
	v_mul_f32_e32 v51, v55, v51
	v_add_f32_e32 v54, 1.0, v54
	v_add_f32_e32 v55, 1.0, v62
	v_rcp_f32_e32 v54, v54
	v_rcp_f32_e32 v55, v55
	v_cvt_pk_bf16_f32 v50, v50, v51
	v_mul_f32_e32 v51, v64, v54
	v_mul_f32_e32 v54, v65, v55
	v_mul_f32_e32 v55, 0xbfb8aa3b, v58
	v_mul_f32_e32 v51, v56, v51
	v_exp_f32_e32 v55, v55
	v_mul_f32_e32 v56, 0xbfb8aa3b, v59
	v_exp_f32_e32 v56, v56
	v_mul_f32_e32 v54, v57, v54
	v_add_f32_e32 v55, 1.0, v55
	v_rcp_f32_e32 v55, v55
	v_add_f32_e32 v56, 1.0, v56
	v_rcp_f32_e32 v56, v56
	v_cvt_pk_bf16_f32 v51, v51, v54
	v_mul_f32_e32 v54, v58, v55
	v_mul_f32_e32 v55, 0xbfb8aa3b, v60
	v_mul_f32_e32 v52, v52, v54
	v_mul_f32_e32 v54, v59, v56
	v_exp_f32_e32 v55, v55
	v_mul_f32_e32 v56, 0xbfb8aa3b, v61
	v_exp_f32_e32 v56, v56
	v_mul_f32_e32 v53, v53, v54
	v_add_f32_e32 v54, 1.0, v55
	v_rcp_f32_e32 v54, v54
	v_add_f32_e32 v55, 1.0, v56
	v_rcp_f32_e32 v55, v55
	v_cvt_pk_bf16_f32 v52, v52, v53
	v_mul_f32_e32 v53, v60, v54
	v_mul_f32_e32 v53, v72, v53
	v_mul_f32_e32 v54, v61, v55
	v_mul_f32_e32 v54, v73, v54
	v_cvt_pk_bf16_f32 v53, v53, v54
	global_store_dwordx4 v[70:71], v[50:53], off
	s_nop 1
	v_add_u32_e32 v50, 0x90, v146
	v_ashrrev_i32_e32 v51, 31, v50
	s_cbranch_vccnz .LBB0_437
	v_readlane_b32 s28, v245, 16
	v_readlane_b32 s29, v245, 17
	s_nop 1
	v_lshl_add_u64 v[52:53], v[50:51], 2, s[28:29]
	global_load_dword v66, v[52:53], off
.LBB0_437:
	s_waitcnt vmcnt(0)
	v_mul_f32_e32 v46, v46, v66
	v_mul_f32_e32 v47, v47, v66
	v_mul_f32_e32 v52, v36, v66
	v_mul_f32_e32 v53, v37, v66
	v_mul_f32_e32 v36, 0xbfb8aa3b, v46
	v_exp_f32_e32 v36, v36
	v_mul_f32_e32 v54, v34, v66
	v_mul_f32_e32 v55, v35, v66
	v_mul_f32_e32 v37, 0xbfb8aa3b, v47
	v_exp_f32_e32 v37, v37
	v_add_f32_e32 v34, 1.0, v36
	v_rcp_f32_e32 v35, v34
	v_mul_f32_e32 v48, v48, v66
	v_mul_f32_e32 v49, v49, v66
	v_mul_f32_e32 v38, v38, v66
	v_mul_f32_e32 v39, v39, v66
	v_add_f32_e32 v34, 1.0, v37
	v_mul_f32_e32 v35, v46, v35
	v_mul_f32_e32 v35, v38, v35
	v_mul_f32_e32 v37, 0xbfb8aa3b, v48
	v_mul_f32_e32 v38, 0xbfb8aa3b, v49
	v_exp_f32_e32 v37, v37
	v_exp_f32_e32 v38, v38
	v_rcp_f32_e32 v36, v34
	v_mul_f32_e32 v42, v42, v66
	v_mul_f32_e32 v43, v43, v66
	v_add_f32_e32 v37, 1.0, v37
	v_add_f32_e32 v38, 1.0, v38
	v_rcp_f32_e32 v37, v37
	v_rcp_f32_e32 v38, v38
	v_mul_f32_e32 v36, v47, v36
	v_mul_f32_e32 v36, v39, v36
	v_cvt_pk_bf16_f32 v36, v35, v36
	v_mul_f32_e32 v35, v48, v37
	v_mul_f32_e32 v37, v49, v38
	v_mul_f32_e32 v38, 0xbfb8aa3b, v42
	v_mul_f32_e32 v39, 0xbfb8aa3b, v43
	v_exp_f32_e32 v38, v38
	v_exp_f32_e32 v39, v39
	v_mul_f32_e32 v40, v40, v66
	v_mul_f32_e32 v41, v41, v66
	v_mul_f32_e32 v44, v44, v66
	v_mul_f32_e32 v45, v45, v66
	v_add_f32_e32 v38, 1.0, v38
	v_add_f32_e32 v39, 1.0, v39
	v_rcp_f32_e32 v38, v38
	v_rcp_f32_e32 v39, v39
	v_mul_f32_e32 v35, v40, v35
	v_mul_f32_e32 v37, v41, v37
	v_cvt_pk_bf16_f32 v37, v35, v37
	v_mul_f32_e32 v35, v42, v38
	v_mul_f32_e32 v38, v43, v39
	v_mul_f32_e32 v39, 0xbfb8aa3b, v44
	v_mul_f32_e32 v40, 0xbfb8aa3b, v45
	v_exp_f32_e32 v39, v39
	v_exp_f32_e32 v40, v40
	v_readlane_b32 s28, v245, 14
	v_lshlrev_b64 v[50:51], 7, v[50:51]
	v_add_f32_e32 v39, 1.0, v39
	v_add_f32_e32 v40, 1.0, v40
	v_rcp_f32_e32 v39, v39
	v_rcp_f32_e32 v40, v40
	v_readlane_b32 s29, v245, 15
	v_mul_f32_e32 v35, v54, v35
	v_mul_f32_e32 v38, v55, v38
	v_lshl_add_u64 v[50:51], s[28:29], 0, v[50:51]
	v_cvt_pk_bf16_f32 v38, v35, v38
	v_mul_f32_e32 v35, v44, v39
	v_mul_f32_e32 v39, v45, v40
	v_lshl_add_u64 v[50:51], v[148:149], 1, v[50:51]
	v_mul_f32_e32 v39, v53, v39
	v_mul_f32_e32 v35, v52, v35
	v_cvt_pk_bf16_f32 v39, v35, v39
	global_store_dwordx4 v[50:51], v[36:39], off
	v_mov_b32_e32 v34, 1.0
	s_and_b64 vcc, exec, s[8:9]
	v_add_u32_e32 v38, 0xa0, v146
	v_ashrrev_i32_e32 v39, 31, v38
	v_mov_b32_e32 v36, 1.0
	s_cbranch_vccnz .LBB0_439
	v_readlane_b32 s28, v245, 16
	v_readlane_b32 s29, v245, 17
	s_nop 1
	v_lshl_add_u64 v[36:37], v[38:39], 2, s[28:29]
	global_load_dword v36, v[36:37], off
.LBB0_439:
	s_waitcnt vmcnt(0)
	v_mul_f32_e32 v30, v30, v36
	v_mul_f32_e32 v31, v31, v36
	v_mul_f32_e32 v32, v32, v36
	v_mul_f32_e32 v33, v33, v36
	v_mul_f32_e32 v28, v28, v36
	v_mul_f32_e32 v29, v29, v36
	v_mul_f32_e32 v26, v26, v36
	v_mul_f32_e32 v27, v27, v36
	v_mul_f32_e32 v24, v24, v36
	v_mul_f32_e32 v25, v25, v36
	v_mul_f32_e32 v22, v22, v36
	v_mul_f32_e32 v23, v23, v36
	v_mul_f32_e32 v35, 0xbfb8aa3b, v30
	v_mul_f32_e32 v37, 0xbfb8aa3b, v31
	v_exp_f32_e32 v35, v35
	v_exp_f32_e32 v37, v37
	v_readlane_b32 s28, v245, 14
	v_lshlrev_b64 v[38:39], 7, v[38:39]
	v_readlane_b32 s29, v245, 15
	v_mul_f32_e32 v40, v20, v36
	v_mul_f32_e32 v41, v21, v36
	v_add_f32_e32 v20, 1.0, v35
	v_rcp_f32_e32 v35, v20
	v_add_f32_e32 v20, 1.0, v37
	v_rcp_f32_e32 v37, v20
	v_lshl_add_u64 v[38:39], s[28:29], 0, v[38:39]
	v_lshl_add_u64 v[38:39], v[148:149], 1, v[38:39]
	s_and_b64 vcc, exec, s[8:9]
	v_mul_f32_e32 v20, v18, v36
	v_mul_f32_e32 v21, v19, v36
	v_mul_f32_e32 v18, v30, v35
	v_mul_f32_e32 v18, v22, v18
	v_mul_f32_e32 v22, 0xbfb8aa3b, v32
	v_mul_f32_e32 v30, 0xbfb8aa3b, v33
	v_exp_f32_e32 v22, v22
	v_exp_f32_e32 v30, v30
	v_mul_f32_e32 v19, v31, v37
	v_mul_f32_e32 v19, v23, v19
	v_add_f32_e32 v22, 1.0, v22
	v_add_f32_e32 v23, 1.0, v30
	v_rcp_f32_e32 v22, v22
	v_rcp_f32_e32 v23, v23
	v_cvt_pk_bf16_f32 v18, v18, v19
	v_mul_f32_e32 v19, v32, v22
	v_mul_f32_e32 v22, v33, v23
	v_mul_f32_e32 v23, 0xbfb8aa3b, v26
	v_mul_f32_e32 v19, v24, v19
	v_exp_f32_e32 v23, v23
	v_mul_f32_e32 v24, 0xbfb8aa3b, v27
	v_exp_f32_e32 v24, v24
	v_mul_f32_e32 v22, v25, v22
	v_add_f32_e32 v23, 1.0, v23
	v_rcp_f32_e32 v23, v23
	v_add_f32_e32 v24, 1.0, v24
	v_rcp_f32_e32 v24, v24
	v_cvt_pk_bf16_f32 v19, v19, v22
	v_mul_f32_e32 v22, v26, v23
	v_mul_f32_e32 v23, 0xbfb8aa3b, v28
	v_mul_f32_e32 v20, v20, v22
	v_mul_f32_e32 v22, v27, v24
	v_exp_f32_e32 v23, v23
	v_mul_f32_e32 v24, 0xbfb8aa3b, v29
	v_exp_f32_e32 v24, v24
	v_mul_f32_e32 v21, v21, v22
	v_add_f32_e32 v22, 1.0, v23
	v_rcp_f32_e32 v22, v22
	v_add_f32_e32 v23, 1.0, v24
	v_rcp_f32_e32 v23, v23
	v_cvt_pk_bf16_f32 v20, v20, v21
	v_mul_f32_e32 v21, v28, v22
	v_mul_f32_e32 v21, v40, v21
	v_mul_f32_e32 v22, v29, v23
	v_mul_f32_e32 v22, v41, v22
	v_cvt_pk_bf16_f32 v21, v21, v22
	global_store_dwordx4 v[38:39], v[18:21], off
	s_nop 1
	v_add_u32_e32 v18, 0xb0, v146
	v_ashrrev_i32_e32 v19, 31, v18
	s_cbranch_vccnz .LBB0_441
	v_readlane_b32 s8, v245, 16
	v_readlane_b32 s9, v245, 17
	s_nop 1
	v_lshl_add_u64 v[20:21], v[18:19], 2, s[8:9]
	global_load_dword v34, v[20:21], off
.LBB0_441:
	s_waitcnt vmcnt(0)
	v_mul_f32_e32 v14, v14, v34
	v_mul_f32_e32 v15, v15, v34
	v_mul_f32_e32 v16, v16, v34
	v_mul_f32_e32 v17, v17, v34
	v_mul_f32_e32 v20, 0xbfb8aa3b, v14
	v_exp_f32_e32 v22, v20
	v_mul_f32_e32 v20, 0xbfb8aa3b, v15
	v_exp_f32_e32 v23, v20
	v_mul_f32_e32 v20, v4, v34
	v_mul_f32_e32 v21, v5, v34
	v_add_f32_e32 v4, 1.0, v22
	v_rcp_f32_e32 v22, v4
	v_add_f32_e32 v4, 1.0, v23
	v_mul_f32_e32 v6, v6, v34
	v_mul_f32_e32 v7, v7, v34
	v_rcp_f32_e32 v23, v4
	v_mul_f32_e32 v4, v2, v34
	v_mul_f32_e32 v5, v3, v34
	v_mul_f32_e32 v2, v14, v22
	v_mul_f32_e32 v2, v6, v2
	v_mul_f32_e32 v6, 0xbfb8aa3b, v16
	v_mul_f32_e32 v14, 0xbfb8aa3b, v17
	v_exp_f32_e32 v6, v6
	v_exp_f32_e32 v14, v14
	v_mul_f32_e32 v3, v15, v23
	v_mul_f32_e32 v3, v7, v3
	v_add_f32_e32 v6, 1.0, v6
	v_add_f32_e32 v7, 1.0, v14
	v_rcp_f32_e32 v6, v6
	v_rcp_f32_e32 v7, v7
	v_mul_f32_e32 v10, v10, v34
	v_mul_f32_e32 v11, v11, v34
	v_mul_f32_e32 v8, v8, v34
	v_mul_f32_e32 v9, v9, v34
	v_cvt_pk_bf16_f32 v2, v2, v3
	v_mul_f32_e32 v3, v16, v6
	v_mul_f32_e32 v6, v17, v7
	v_mul_f32_e32 v7, 0xbfb8aa3b, v10
	v_mul_f32_e32 v3, v8, v3
	v_exp_f32_e32 v7, v7
	v_mul_f32_e32 v8, 0xbfb8aa3b, v11
	v_exp_f32_e32 v8, v8
	v_mul_f32_e32 v12, v12, v34
	v_mul_f32_e32 v13, v13, v34
	v_add_f32_e32 v7, 1.0, v7
	v_rcp_f32_e32 v7, v7
	v_add_f32_e32 v8, 1.0, v8
	v_rcp_f32_e32 v8, v8
	v_mul_f32_e32 v6, v9, v6
	v_cvt_pk_bf16_f32 v3, v3, v6
	v_mul_f32_e32 v6, v10, v7
	v_mul_f32_e32 v7, 0xbfb8aa3b, v12
	v_mul_f32_e32 v4, v4, v6
	v_mul_f32_e32 v6, v11, v8
	v_exp_f32_e32 v7, v7
	v_mul_f32_e32 v8, 0xbfb8aa3b, v13
	v_exp_f32_e32 v8, v8
	v_mul_f32_e32 v5, v5, v6
	v_add_f32_e32 v6, 1.0, v7
	v_rcp_f32_e32 v6, v6
	v_add_f32_e32 v7, 1.0, v8
	v_rcp_f32_e32 v7, v7
	v_readlane_b32 s8, v245, 14
	v_lshlrev_b64 v[18:19], 7, v[18:19]
	v_readlane_b32 s9, v245, 15
	v_cvt_pk_bf16_f32 v4, v4, v5
	v_mul_f32_e32 v5, v12, v6
	v_mul_f32_e32 v5, v20, v5
	v_lshl_add_u64 v[18:19], s[8:9], 0, v[18:19]
	v_lshl_add_u64 v[18:19], v[148:149], 1, v[18:19]
	v_mul_f32_e32 v6, v13, v7
	s_andn2_b64 vcc, exec, s[6:7]
	s_mov_b64 s[6:7], -1
	v_mul_f32_e32 v6, v21, v6
	v_cvt_pk_bf16_f32 v5, v5, v6
	global_store_dwordx4 v[18:19], v[2:5], off
	s_cbranch_vccnz .LBB0_418
	s_andn2_b64 vcc, exec, s[2:3]
	s_cbranch_vccnz .LBB0_417
	s_barrier
	s_branch .LBB0_417

.LBB0_804:
	s_ashr_i32 s5, s4, 3
	s_cmp_lt_i32 s5, 2
	s_cselect_b64 s[12:13], -1, 0
	s_lshl_b32 s2, s2, 8
	v_mov_b32_e32 v130, v176
	s_add_i32 s2, s2, s37
	s_and_b64 s[26:27], s[16:17], s[12:13]
	v_and_or_b32 v158, v130, 15, s2
	v_readlane_b32 s2, v245, 16
	v_ashrrev_i32_e32 v159, 31, v158
	v_readlane_b32 s3, v245, 17
	v_bfe_u32 v146, v130, 4, 2
	v_cmp_eq_u32_e32 vcc, 0, v146
	v_lshl_add_u64 v[160:161], v[158:159], 2, s[2:3]
	global_load_dword v162, v[160:161], off
	v_cndmask_b32_e64 v156, 1.0, -1.0, vcc
	v_cmp_gt_u32_e32 vcc, 2, v146
	v_mov_b32_e32 v134, 1.0
	s_and_b64 s[2:3], s[26:27], vcc
	v_mov_b32_e32 v157, v156
	v_mov_b32_e32 v168, 0
	v_mov_b32_e32 v135, 1.0
	v_mov_b32_e32 v136, 1.0
	v_mov_b32_e32 v137, 1.0
	v_mov_b32_e32 v130, 1.0
	v_mov_b32_e32 v131, 1.0
	v_mov_b32_e32 v132, 1.0
	v_mov_b32_e32 v133, 1.0
	v_mov_b32_e32 v169, 0
	v_mov_b32_e32 v170, 0
	v_mov_b32_e32 v171, 0
	v_mov_b32_e32 v166, 0
	v_mov_b32_e32 v167, 0
	v_mov_b32_e32 v164, 0
	v_mov_b32_e32 v165, 0
	s_and_saveexec_b64 s[12:13], s[2:3]
	s_cbranch_execz .LBB0_806
	v_lshlrev_b64 v[130:131], 6, v[158:159]
	v_lshl_add_u64 v[130:131], s[14:15], 0, v[130:131]
	global_load_dwordx4 v[164:167], v[130:131], off offset:32
	global_load_dwordx4 v[172:175], v[130:131], off offset:48
	global_load_dwordx4 v[134:137], v[130:131], off
	s_nop 0
	global_load_dwordx4 v[130:133], v[130:131], off offset:16
	v_mov_b32_e32 v186, v156
	v_mov_b32_e32 v187, v156
	s_waitcnt vmcnt(0)
	v_mul_f32_e32 v170, v186, v166
	v_mul_f32_e32 v171, v187, v167
	v_mul_f32_e32 v168, v156, v164
	v_mul_f32_e32 v169, v157, v165
	v_mul_f32_e32 v164, v186, v174
	v_mul_f32_e32 v165, v187, v175
	v_mul_f32_e32 v166, v156, v172
	v_mul_f32_e32 v167, v157, v173
.LBB0_806:
	s_or_b64 exec, exec, s[12:13]
	v_cndmask_b32_e64 v163, 0, 1, s[26:27]
	v_cmp_ne_u32_e64 s[12:13], 1, v163
	s_andn2_b64 vcc, exec, s[26:27]
	s_cbranch_vccnz .LBB0_808
	v_and_b32_e32 v172, 64, v182
	v_xor_b32_e32 v163, 16, v182
	v_add_u32_e32 v172, 64, v172
	v_cmp_lt_i32_e32 vcc, v163, v172
	s_nop 1
	v_cndmask_b32_e32 v163, v182, v163, vcc
	v_lshlrev_b32_e32 v163, 2, v163
	ds_bpermute_b32 v172, v163, v126
	ds_bpermute_b32 v173, v163, v127
	ds_bpermute_b32 v174, v163, v122
	ds_bpermute_b32 v186, v163, v128
	ds_bpermute_b32 v187, v163, v129
	ds_bpermute_b32 v175, v163, v123
	ds_bpermute_b32 v188, v163, v124
	ds_bpermute_b32 v189, v163, v125
	s_waitcnt lgkmcnt(0)
	v_mul_f32_e32 v172, v168, v172
	v_mul_f32_e32 v173, v169, v173
	v_mul_f32_e32 v186, v170, v186
	v_mul_f32_e32 v187, v171, v187
	v_fma_f32 v126, v126, v134, v172
	v_fma_f32 v127, v127, v135, v173
	v_mul_f32_e32 v172, v166, v174
	v_mul_f32_e32 v173, v167, v175
	v_mul_f32_e32 v174, v164, v188
	v_mul_f32_e32 v175, v165, v189
	v_fma_f32 v128, v128, v136, v186
	v_fma_f32 v129, v129, v137, v187
	v_fma_f32 v124, v124, v132, v174
	v_fma_f32 v125, v125, v133, v175
	v_fma_f32 v122, v122, v130, v172
	v_fma_f32 v123, v123, v131, v173
.LBB0_808:
	s_cmp_eq_u32 s5, 3
	s_cselect_b64 vcc, -1, 0
	s_cmp_gt_u32 s4, 7
	v_cndmask_b32_e32 v163, 1.0, v183, vcc
	s_cselect_b64 vcc, -1, 0
	s_lshl_b32 s4, s4, 1
	s_lshl_b32 s5, s5, 4
	s_and_b32 s4, s4, 14
	s_or_b32 s4, s5, s4
	s_ashr_i32 s5, s4, 31
	s_lshl_b64 s[4:5], s[4:5], 21
	s_add_u32 s4, s40, s4
	v_cndmask_b32_e32 v185, v184, v163, vcc
	s_addc_u32 s5, s41, s5
	v_lshlrev_b32_e32 v146, 4, v146
	s_waitcnt vmcnt(0)
	v_mul_f32_e32 v174, v185, v162
	v_lshl_add_u64 v[162:163], s[4:5], 0, v[146:147]
	v_lshlrev_b64 v[172:173], 8, v[158:159]
	v_lshl_add_u64 v[172:173], v[162:163], 0, v[172:173]
	v_mul_f32_e32 v186, v174, v124
	v_mul_f32_e32 v187, v174, v125
	v_mul_f32_e32 v124, v174, v122
	v_mul_f32_e32 v125, v174, v123
	s_and_b64 vcc, exec, s[12:13]
	v_mul_f32_e32 v128, v174, v128
	v_mul_f32_e32 v129, v174, v129
	v_mul_f32_e32 v126, v174, v126
	v_mul_f32_e32 v127, v174, v127
	v_cvt_pk_bf16_f32 v122, v126, v127
	v_cvt_pk_bf16_f32 v123, v128, v129
	v_cvt_pk_bf16_f32 v124, v124, v125
	v_cvt_pk_bf16_f32 v125, v186, v187
	global_store_dwordx4 v[172:173], v[122:125], off
	s_cbranch_vccnz .LBB0_810
	s_nop 0
	v_and_b32_e32 v123, 64, v182
	v_xor_b32_e32 v122, 16, v182
	v_add_u32_e32 v123, 64, v123
	v_cmp_lt_i32_e32 vcc, v122, v123
	s_nop 1
	v_cndmask_b32_e32 v122, v182, v122, vcc
	v_lshlrev_b32_e32 v129, 2, v122
	ds_bpermute_b32 v122, v129, v118
	ds_bpermute_b32 v123, v129, v119
	ds_bpermute_b32 v124, v129, v114
	ds_bpermute_b32 v126, v129, v120
	ds_bpermute_b32 v127, v129, v121
	ds_bpermute_b32 v125, v129, v115
	ds_bpermute_b32 v128, v129, v116
	ds_bpermute_b32 v129, v129, v117
	s_waitcnt lgkmcnt(6)
	v_mul_f32_e32 v122, v168, v122
	v_mul_f32_e32 v123, v169, v123
	s_waitcnt lgkmcnt(3)
	v_mul_f32_e32 v126, v170, v126
	v_mul_f32_e32 v127, v171, v127
	v_fma_f32 v118, v118, v134, v122
	v_fma_f32 v119, v119, v135, v123
	s_waitcnt lgkmcnt(2)
	v_mul_f32_e32 v122, v166, v124
	v_mul_f32_e32 v123, v167, v125
	s_waitcnt lgkmcnt(0)
	v_mul_f32_e32 v124, v164, v128
	v_mul_f32_e32 v125, v165, v129
	v_fma_f32 v120, v120, v136, v126
	v_fma_f32 v121, v121, v137, v127
	v_fma_f32 v116, v116, v132, v124
	v_fma_f32 v117, v117, v133, v125
	v_fma_f32 v114, v114, v130, v122
	v_fma_f32 v115, v115, v131, v123
.LBB0_810:
	v_mov_b32_e32 v175, v174
	v_mov_b32_e32 v122, v174
	v_mov_b32_e32 v123, v174
	v_mul_f32_e32 v118, v174, v118
	v_mul_f32_e32 v119, v175, v119
	v_mul_f32_e32 v120, v122, v120
	v_mul_f32_e32 v121, v123, v121
	v_mul_f32_e32 v122, v122, v116
	v_mul_f32_e32 v123, v123, v117
	v_mul_f32_e32 v116, v174, v114
	v_mul_f32_e32 v117, v175, v115
	v_cvt_pk_bf16_f32 v114, v118, v119
	v_add_co_u32_e32 v118, vcc, s44, v172
	v_or_b32_e32 v130, 16, v158
	s_nop 0
	v_addc_co_u32_e32 v119, vcc, 0, v173, vcc
	v_readlane_b32 s4, v245, 16
	v_cvt_pk_bf16_f32 v115, v120, v121
	v_cvt_pk_bf16_f32 v116, v116, v117
	v_cvt_pk_bf16_f32 v117, v122, v123
	global_store_dwordx4 v[118:119], v[114:117], off
	v_ashrrev_i32_e32 v131, 31, v130
	v_readlane_b32 s5, v245, 17
	v_mov_b32_e32 v126, 0
	v_mov_b32_e32 v118, 1.0
	v_lshl_add_u64 v[114:115], v[130:131], 2, s[4:5]
	global_load_dword v132, v[114:115], off
	v_mov_b32_e32 v119, 1.0
	v_mov_b32_e32 v120, 1.0
	v_mov_b32_e32 v121, 1.0
	v_mov_b32_e32 v114, 1.0
	v_mov_b32_e32 v115, 1.0
	v_mov_b32_e32 v116, 1.0
	v_mov_b32_e32 v117, 1.0
	v_mov_b32_e32 v127, 0
	v_mov_b32_e32 v128, 0
	v_mov_b32_e32 v129, 0
	v_mov_b32_e32 v124, 0
	v_mov_b32_e32 v125, 0
	v_mov_b32_e32 v122, 0
	v_mov_b32_e32 v123, 0
	s_and_saveexec_b64 s[4:5], s[2:3]
	s_cbranch_execz .LBB0_812
	v_lshlrev_b64 v[114:115], 6, v[130:131]
	v_lshl_add_u64 v[114:115], s[14:15], 0, v[114:115]
	global_load_dwordx4 v[122:125], v[114:115], off offset:32
	global_load_dwordx4 v[134:137], v[114:115], off offset:48
	global_load_dwordx4 v[118:121], v[114:115], off
	s_nop 0
	global_load_dwordx4 v[114:117], v[114:115], off offset:16
	v_mov_b32_e32 v164, v156
	v_mov_b32_e32 v165, v156
	s_waitcnt vmcnt(3)
	v_mul_f32_e32 v128, v164, v124
	v_mul_f32_e32 v129, v165, v125
	v_mul_f32_e32 v126, v156, v122
	v_mul_f32_e32 v127, v157, v123
	s_waitcnt vmcnt(2)
	v_mul_f32_e32 v122, v164, v136
	v_mul_f32_e32 v123, v165, v137
	v_mul_f32_e32 v124, v156, v134
	v_mul_f32_e32 v125, v157, v135
.LBB0_812:
	s_or_b64 exec, exec, s[4:5]
	s_and_b64 vcc, exec, s[12:13]
	s_cbranch_vccnz .LBB0_814
	v_and_b32_e32 v134, 64, v182
	v_xor_b32_e32 v133, 16, v182
	v_add_u32_e32 v134, 64, v134
	v_cmp_lt_i32_e32 vcc, v133, v134
	s_nop 1
	v_cndmask_b32_e32 v133, v182, v133, vcc
	v_lshlrev_b32_e32 v133, 2, v133
	ds_bpermute_b32 v134, v133, v110
	ds_bpermute_b32 v135, v133, v111
	ds_bpermute_b32 v136, v133, v106
	ds_bpermute_b32 v164, v133, v112
	ds_bpermute_b32 v165, v133, v113
	ds_bpermute_b32 v137, v133, v107
	ds_bpermute_b32 v166, v133, v108
	ds_bpermute_b32 v167, v133, v109
	s_waitcnt lgkmcnt(6)
	v_mul_f32_e32 v134, v126, v134
	v_mul_f32_e32 v135, v127, v135
	s_waitcnt lgkmcnt(3)
	v_mul_f32_e32 v164, v128, v164
	v_mul_f32_e32 v165, v129, v165
	s_waitcnt vmcnt(1)
	v_fma_f32 v110, v110, v118, v134
	v_fma_f32 v111, v111, v119, v135
	s_waitcnt lgkmcnt(2)
	v_mul_f32_e32 v134, v124, v136
	v_mul_f32_e32 v135, v125, v137
	s_waitcnt lgkmcnt(0)
	v_mul_f32_e32 v136, v122, v166
	v_mul_f32_e32 v137, v123, v167
	v_fma_f32 v112, v112, v120, v164
	v_fma_f32 v113, v113, v121, v165
	s_waitcnt vmcnt(0)
	v_fma_f32 v108, v108, v116, v136
	v_fma_f32 v109, v109, v117, v137
	v_fma_f32 v106, v106, v114, v134
	v_fma_f32 v107, v107, v115, v135
.LBB0_814:
	s_waitcnt vmcnt(0)
	v_mul_f32_e32 v132, v185, v132
	v_lshlrev_b64 v[130:131], 8, v[130:131]
	v_lshl_add_u64 v[130:131], v[162:163], 0, v[130:131]
	v_mul_f32_e32 v134, v132, v108
	v_mul_f32_e32 v135, v132, v109
	v_mul_f32_e32 v108, v132, v106
	v_mul_f32_e32 v109, v132, v107
	s_and_b64 vcc, exec, s[12:13]
	v_mul_f32_e32 v112, v132, v112
	v_mul_f32_e32 v113, v132, v113
	v_mul_f32_e32 v110, v132, v110
	v_mul_f32_e32 v111, v132, v111
	v_cvt_pk_bf16_f32 v106, v110, v111
	v_cvt_pk_bf16_f32 v107, v112, v113
	v_cvt_pk_bf16_f32 v108, v108, v109
	v_cvt_pk_bf16_f32 v109, v134, v135
	global_store_dwordx4 v[130:131], v[106:109], off
	s_cbranch_vccnz .LBB0_816
	s_nop 0
	v_and_b32_e32 v107, 64, v182
	v_xor_b32_e32 v106, 16, v182
	v_add_u32_e32 v107, 64, v107
	v_cmp_lt_i32_e32 vcc, v106, v107
	s_nop 1
	v_cndmask_b32_e32 v106, v182, v106, vcc
	v_lshlrev_b32_e32 v113, 2, v106
	ds_bpermute_b32 v106, v113, v102
	ds_bpermute_b32 v107, v113, v103
	ds_bpermute_b32 v108, v113, v98
	ds_bpermute_b32 v110, v113, v104
	ds_bpermute_b32 v111, v113, v105
	ds_bpermute_b32 v109, v113, v99
	ds_bpermute_b32 v112, v113, v100
	ds_bpermute_b32 v113, v113, v101
	s_waitcnt lgkmcnt(6)
	v_mul_f32_e32 v106, v126, v106
	v_mul_f32_e32 v107, v127, v107
	s_waitcnt lgkmcnt(3)
	v_mul_f32_e32 v110, v128, v110
	v_mul_f32_e32 v111, v129, v111
	v_fma_f32 v102, v102, v118, v106
	v_fma_f32 v103, v103, v119, v107
	s_waitcnt lgkmcnt(2)
	v_mul_f32_e32 v106, v124, v108
	v_mul_f32_e32 v107, v125, v109
	s_waitcnt lgkmcnt(0)
	v_mul_f32_e32 v108, v122, v112
	v_mul_f32_e32 v109, v123, v113
	v_fma_f32 v104, v104, v120, v110
	v_fma_f32 v105, v105, v121, v111
	v_fma_f32 v100, v100, v116, v108
	v_fma_f32 v101, v101, v117, v109
	v_fma_f32 v98, v98, v114, v106
	v_fma_f32 v99, v99, v115, v107
.LBB0_816:
	v_mov_b32_e32 v133, v132
	v_mov_b32_e32 v106, v132
	v_mov_b32_e32 v107, v132
	v_mul_f32_e32 v102, v132, v102
	v_mul_f32_e32 v103, v133, v103
	v_mul_f32_e32 v104, v106, v104
	v_mul_f32_e32 v105, v107, v105
	v_mul_f32_e32 v106, v106, v100
	v_mul_f32_e32 v107, v107, v101
	v_mul_f32_e32 v100, v132, v98
	v_mul_f32_e32 v101, v133, v99
	v_cvt_pk_bf16_f32 v98, v102, v103
	v_add_co_u32_e32 v102, vcc, s44, v130
	v_or_b32_e32 v114, 32, v158
	s_nop 0
	v_addc_co_u32_e32 v103, vcc, 0, v131, vcc
	v_readlane_b32 s4, v245, 16
	v_cvt_pk_bf16_f32 v99, v104, v105
	v_cvt_pk_bf16_f32 v100, v100, v101
	v_cvt_pk_bf16_f32 v101, v106, v107
	global_store_dwordx4 v[102:103], v[98:101], off
	v_ashrrev_i32_e32 v115, 31, v114
	v_readlane_b32 s5, v245, 17
	v_mov_b32_e32 v110, 0
	v_mov_b32_e32 v102, 1.0
	v_lshl_add_u64 v[98:99], v[114:115], 2, s[4:5]
	global_load_dword v116, v[98:99], off
	v_mov_b32_e32 v103, 1.0
	v_mov_b32_e32 v104, 1.0
	v_mov_b32_e32 v105, 1.0
	v_mov_b32_e32 v98, 1.0
	v_mov_b32_e32 v99, 1.0
	v_mov_b32_e32 v100, 1.0
	v_mov_b32_e32 v101, 1.0
	v_mov_b32_e32 v111, 0
	v_mov_b32_e32 v112, 0
	v_mov_b32_e32 v113, 0
	v_mov_b32_e32 v108, 0
	v_mov_b32_e32 v109, 0
	v_mov_b32_e32 v106, 0
	v_mov_b32_e32 v107, 0
	s_and_saveexec_b64 s[4:5], s[2:3]
	s_cbranch_execz .LBB0_818
	v_lshlrev_b64 v[98:99], 6, v[114:115]
	v_lshl_add_u64 v[98:99], s[14:15], 0, v[98:99]
	global_load_dwordx4 v[106:109], v[98:99], off offset:32
	global_load_dwordx4 v[118:121], v[98:99], off offset:48
	global_load_dwordx4 v[102:105], v[98:99], off
	s_nop 0
	global_load_dwordx4 v[98:101], v[98:99], off offset:16
	v_mov_b32_e32 v122, v156
	v_mov_b32_e32 v123, v156
	s_waitcnt vmcnt(3)
	v_mul_f32_e32 v112, v122, v108
	v_mul_f32_e32 v113, v123, v109
	v_mul_f32_e32 v110, v156, v106
	v_mul_f32_e32 v111, v157, v107
	s_waitcnt vmcnt(2)
	v_mul_f32_e32 v106, v122, v120
	v_mul_f32_e32 v107, v123, v121
	v_mul_f32_e32 v108, v156, v118
	v_mul_f32_e32 v109, v157, v119
.LBB0_818:
	s_or_b64 exec, exec, s[4:5]
	s_and_b64 vcc, exec, s[12:13]
	s_cbranch_vccnz .LBB0_820
	v_and_b32_e32 v118, 64, v182
	v_xor_b32_e32 v117, 16, v182
	v_add_u32_e32 v118, 64, v118
	v_cmp_lt_i32_e32 vcc, v117, v118
	s_nop 1
	v_cndmask_b32_e32 v117, v182, v117, vcc
	v_lshlrev_b32_e32 v117, 2, v117
	ds_bpermute_b32 v118, v117, v94
	ds_bpermute_b32 v119, v117, v95
	ds_bpermute_b32 v120, v117, v90
	ds_bpermute_b32 v122, v117, v96
	ds_bpermute_b32 v123, v117, v97
	ds_bpermute_b32 v121, v117, v91
	ds_bpermute_b32 v124, v117, v92
	ds_bpermute_b32 v125, v117, v93
	s_waitcnt lgkmcnt(6)
	v_mul_f32_e32 v118, v110, v118
	v_mul_f32_e32 v119, v111, v119
	s_waitcnt lgkmcnt(3)
	v_mul_f32_e32 v122, v112, v122
	v_mul_f32_e32 v123, v113, v123
	s_waitcnt vmcnt(1)
	v_fma_f32 v94, v94, v102, v118
	v_fma_f32 v95, v95, v103, v119
	s_waitcnt lgkmcnt(2)
	v_mul_f32_e32 v118, v108, v120
	v_mul_f32_e32 v119, v109, v121
	s_waitcnt lgkmcnt(0)
	v_mul_f32_e32 v120, v106, v124
	v_mul_f32_e32 v121, v107, v125
	v_fma_f32 v96, v96, v104, v122
	v_fma_f32 v97, v97, v105, v123
	s_waitcnt vmcnt(0)
	v_fma_f32 v92, v92, v100, v120
	v_fma_f32 v93, v93, v101, v121
	v_fma_f32 v90, v90, v98, v118
	v_fma_f32 v91, v91, v99, v119
.LBB0_820:
	s_waitcnt vmcnt(0)
	v_mul_f32_e32 v116, v185, v116
	v_lshlrev_b64 v[114:115], 8, v[114:115]
	v_lshl_add_u64 v[114:115], v[162:163], 0, v[114:115]
	v_mul_f32_e32 v118, v116, v92
	v_mul_f32_e32 v119, v116, v93
	v_mul_f32_e32 v92, v116, v90
	v_mul_f32_e32 v93, v116, v91
	s_and_b64 vcc, exec, s[12:13]
	v_mul_f32_e32 v96, v116, v96
	v_mul_f32_e32 v97, v116, v97
	v_mul_f32_e32 v94, v116, v94
	v_mul_f32_e32 v95, v116, v95
	v_cvt_pk_bf16_f32 v90, v94, v95
	v_cvt_pk_bf16_f32 v91, v96, v97
	v_cvt_pk_bf16_f32 v92, v92, v93
	v_cvt_pk_bf16_f32 v93, v118, v119
	global_store_dwordx4 v[114:115], v[90:93], off
	s_cbranch_vccnz .LBB0_822
	s_nop 0
	v_and_b32_e32 v91, 64, v182
	v_xor_b32_e32 v90, 16, v182
	v_add_u32_e32 v91, 64, v91
	v_cmp_lt_i32_e32 vcc, v90, v91
	s_nop 1
	v_cndmask_b32_e32 v90, v182, v90, vcc
	v_lshlrev_b32_e32 v97, 2, v90
	ds_bpermute_b32 v90, v97, v86
	ds_bpermute_b32 v91, v97, v87
	ds_bpermute_b32 v92, v97, v82
	ds_bpermute_b32 v94, v97, v88
	ds_bpermute_b32 v95, v97, v89
	ds_bpermute_b32 v93, v97, v83
	ds_bpermute_b32 v96, v97, v84
	ds_bpermute_b32 v97, v97, v85
	s_waitcnt lgkmcnt(6)
	v_mul_f32_e32 v90, v110, v90
	v_mul_f32_e32 v91, v111, v91
	s_waitcnt lgkmcnt(3)
	v_mul_f32_e32 v94, v112, v94
	v_mul_f32_e32 v95, v113, v95
	v_fma_f32 v86, v86, v102, v90
	v_fma_f32 v87, v87, v103, v91
	s_waitcnt lgkmcnt(2)
	v_mul_f32_e32 v90, v108, v92
	v_mul_f32_e32 v91, v109, v93
	s_waitcnt lgkmcnt(0)
	v_mul_f32_e32 v92, v106, v96
	v_mul_f32_e32 v93, v107, v97
	v_fma_f32 v88, v88, v104, v94
	v_fma_f32 v89, v89, v105, v95
	v_fma_f32 v84, v84, v100, v92
	v_fma_f32 v85, v85, v101, v93
	v_fma_f32 v82, v82, v98, v90
	v_fma_f32 v83, v83, v99, v91
.LBB0_822:
	v_mov_b32_e32 v117, v116
	v_mov_b32_e32 v90, v116
	v_mov_b32_e32 v91, v116
	v_mul_f32_e32 v86, v116, v86
	v_mul_f32_e32 v87, v117, v87
	v_mul_f32_e32 v88, v90, v88
	v_mul_f32_e32 v89, v91, v89
	v_mul_f32_e32 v90, v90, v84
	v_mul_f32_e32 v91, v91, v85
	v_mul_f32_e32 v84, v116, v82
	v_mul_f32_e32 v85, v117, v83
	v_cvt_pk_bf16_f32 v82, v86, v87
	v_add_co_u32_e32 v86, vcc, s44, v114
	v_or_b32_e32 v98, 48, v158
	s_nop 0
	v_addc_co_u32_e32 v87, vcc, 0, v115, vcc
	v_readlane_b32 s4, v245, 16
	v_cvt_pk_bf16_f32 v83, v88, v89
	v_cvt_pk_bf16_f32 v84, v84, v85
	v_cvt_pk_bf16_f32 v85, v90, v91
	global_store_dwordx4 v[86:87], v[82:85], off
	v_ashrrev_i32_e32 v99, 31, v98
	v_readlane_b32 s5, v245, 17
	v_mov_b32_e32 v94, 0
	v_mov_b32_e32 v86, 1.0
	v_lshl_add_u64 v[82:83], v[98:99], 2, s[4:5]
	global_load_dword v100, v[82:83], off
	v_mov_b32_e32 v87, 1.0
	v_mov_b32_e32 v88, 1.0
	v_mov_b32_e32 v89, 1.0
	v_mov_b32_e32 v82, 1.0
	v_mov_b32_e32 v83, 1.0
	v_mov_b32_e32 v84, 1.0
	v_mov_b32_e32 v85, 1.0
	v_mov_b32_e32 v95, 0
	v_mov_b32_e32 v96, 0
	v_mov_b32_e32 v97, 0
	v_mov_b32_e32 v92, 0
	v_mov_b32_e32 v93, 0
	v_mov_b32_e32 v90, 0
	v_mov_b32_e32 v91, 0
	s_and_saveexec_b64 s[4:5], s[2:3]
	s_cbranch_execz .LBB0_824
	v_lshlrev_b64 v[82:83], 6, v[98:99]
	v_lshl_add_u64 v[82:83], s[14:15], 0, v[82:83]
	global_load_dwordx4 v[90:93], v[82:83], off offset:32
	global_load_dwordx4 v[102:105], v[82:83], off offset:48
	global_load_dwordx4 v[86:89], v[82:83], off
	s_nop 0
	global_load_dwordx4 v[82:85], v[82:83], off offset:16
	v_mov_b32_e32 v106, v156
	v_mov_b32_e32 v107, v156
	s_waitcnt vmcnt(3)
	v_mul_f32_e32 v96, v106, v92
	v_mul_f32_e32 v97, v107, v93
	v_mul_f32_e32 v94, v156, v90
	v_mul_f32_e32 v95, v157, v91
	s_waitcnt vmcnt(2)
	v_mul_f32_e32 v90, v106, v104
	v_mul_f32_e32 v91, v107, v105
	v_mul_f32_e32 v92, v156, v102
	v_mul_f32_e32 v93, v157, v103
.LBB0_824:
	s_or_b64 exec, exec, s[4:5]
	s_and_b64 vcc, exec, s[12:13]
	s_cbranch_vccnz .LBB0_826
	v_and_b32_e32 v102, 64, v182
	v_xor_b32_e32 v101, 16, v182
	v_add_u32_e32 v102, 64, v102
	v_cmp_lt_i32_e32 vcc, v101, v102
	s_nop 1
	v_cndmask_b32_e32 v101, v182, v101, vcc
	v_lshlrev_b32_e32 v101, 2, v101
	ds_bpermute_b32 v102, v101, v78
	ds_bpermute_b32 v103, v101, v79
	ds_bpermute_b32 v104, v101, v74
	ds_bpermute_b32 v106, v101, v80
	ds_bpermute_b32 v107, v101, v81
	ds_bpermute_b32 v105, v101, v75
	ds_bpermute_b32 v108, v101, v76
	ds_bpermute_b32 v109, v101, v77
	s_waitcnt lgkmcnt(6)
	v_mul_f32_e32 v102, v94, v102
	v_mul_f32_e32 v103, v95, v103
	s_waitcnt lgkmcnt(3)
	v_mul_f32_e32 v106, v96, v106
	v_mul_f32_e32 v107, v97, v107
	s_waitcnt vmcnt(1)
	v_fma_f32 v78, v78, v86, v102
	v_fma_f32 v79, v79, v87, v103
	s_waitcnt lgkmcnt(2)
	v_mul_f32_e32 v102, v92, v104
	v_mul_f32_e32 v103, v93, v105
	s_waitcnt lgkmcnt(0)
	v_mul_f32_e32 v104, v90, v108
	v_mul_f32_e32 v105, v91, v109
	v_fma_f32 v80, v80, v88, v106
	v_fma_f32 v81, v81, v89, v107
	s_waitcnt vmcnt(0)
	v_fma_f32 v76, v76, v84, v104
	v_fma_f32 v77, v77, v85, v105
	v_fma_f32 v74, v74, v82, v102
	v_fma_f32 v75, v75, v83, v103
.LBB0_826:
	s_waitcnt vmcnt(0)
	v_mul_f32_e32 v100, v185, v100
	v_lshlrev_b64 v[98:99], 8, v[98:99]
	v_lshl_add_u64 v[98:99], v[162:163], 0, v[98:99]
	v_mul_f32_e32 v102, v100, v76
	v_mul_f32_e32 v103, v100, v77
	v_mul_f32_e32 v76, v100, v74
	v_mul_f32_e32 v77, v100, v75
	s_and_b64 vcc, exec, s[12:13]
	v_mul_f32_e32 v80, v100, v80
	v_mul_f32_e32 v81, v100, v81
	v_mul_f32_e32 v78, v100, v78
	v_mul_f32_e32 v79, v100, v79
	v_cvt_pk_bf16_f32 v74, v78, v79
	v_cvt_pk_bf16_f32 v75, v80, v81
	v_cvt_pk_bf16_f32 v76, v76, v77
	v_cvt_pk_bf16_f32 v77, v102, v103
	global_store_dwordx4 v[98:99], v[74:77], off
	s_cbranch_vccnz .LBB0_828
	s_nop 0
	v_and_b32_e32 v75, 64, v182
	v_xor_b32_e32 v74, 16, v182
	v_add_u32_e32 v75, 64, v75
	v_cmp_lt_i32_e32 vcc, v74, v75
	s_nop 1
	v_cndmask_b32_e32 v74, v182, v74, vcc
	v_lshlrev_b32_e32 v81, 2, v74
	ds_bpermute_b32 v74, v81, v70
	ds_bpermute_b32 v75, v81, v71
	ds_bpermute_b32 v76, v81, v66
	ds_bpermute_b32 v78, v81, v72
	ds_bpermute_b32 v79, v81, v73
	ds_bpermute_b32 v77, v81, v67
	ds_bpermute_b32 v80, v81, v68
	ds_bpermute_b32 v81, v81, v69
	s_waitcnt lgkmcnt(6)
	v_mul_f32_e32 v74, v94, v74
	v_mul_f32_e32 v75, v95, v75
	s_waitcnt lgkmcnt(3)
	v_mul_f32_e32 v78, v96, v78
	v_mul_f32_e32 v79, v97, v79
	v_fma_f32 v70, v70, v86, v74
	v_fma_f32 v71, v71, v87, v75
	s_waitcnt lgkmcnt(2)
	v_mul_f32_e32 v74, v92, v76
	v_mul_f32_e32 v75, v93, v77
	s_waitcnt lgkmcnt(0)
	v_mul_f32_e32 v76, v90, v80
	v_mul_f32_e32 v77, v91, v81
	v_fma_f32 v72, v72, v88, v78
	v_fma_f32 v73, v73, v89, v79
	v_fma_f32 v68, v68, v84, v76
	v_fma_f32 v69, v69, v85, v77
	v_fma_f32 v66, v66, v82, v74
	v_fma_f32 v67, v67, v83, v75
.LBB0_828:
	v_mov_b32_e32 v101, v100
	v_mov_b32_e32 v74, v100
	v_mov_b32_e32 v75, v100
	v_mul_f32_e32 v70, v100, v70
	v_mul_f32_e32 v71, v101, v71
	v_mul_f32_e32 v72, v74, v72
	v_mul_f32_e32 v73, v75, v73
	v_mul_f32_e32 v74, v74, v68
	v_mul_f32_e32 v75, v75, v69
	v_mul_f32_e32 v68, v100, v66
	v_mul_f32_e32 v69, v101, v67
	v_cvt_pk_bf16_f32 v66, v70, v71
	v_add_co_u32_e32 v70, vcc, s44, v98
	v_cvt_pk_bf16_f32 v67, v72, v73
	v_cvt_pk_bf16_f32 v68, v68, v69
	v_cvt_pk_bf16_f32 v69, v74, v75
	v_add_u32_e32 v82, 0x80, v158
	s_nop 0
	v_addc_co_u32_e32 v71, vcc, 0, v99, vcc
	global_store_dwordx4 v[70:71], v[66:69], off
	global_load_dword v84, v[160:161], off offset:512
	v_ashrrev_i32_e32 v83, 31, v82
	v_mov_b32_e32 v78, 0
	v_mov_b32_e32 v70, 1.0
	v_mov_b32_e32 v71, 1.0
	v_mov_b32_e32 v72, 1.0
	v_mov_b32_e32 v73, 1.0
	v_mov_b32_e32 v66, 1.0
	v_mov_b32_e32 v67, 1.0
	v_mov_b32_e32 v68, 1.0
	v_mov_b32_e32 v69, 1.0
	v_mov_b32_e32 v79, 0
	v_mov_b32_e32 v80, 0
	v_mov_b32_e32 v81, 0
	v_mov_b32_e32 v76, 0
	v_mov_b32_e32 v77, 0
	v_mov_b32_e32 v74, 0
	v_mov_b32_e32 v75, 0
	s_and_saveexec_b64 s[4:5], s[2:3]
	s_cbranch_execz .LBB0_830
	v_lshlrev_b64 v[66:67], 6, v[82:83]
	v_lshl_add_u64 v[66:67], s[14:15], 0, v[66:67]
	global_load_dwordx4 v[74:77], v[66:67], off offset:32
	global_load_dwordx4 v[86:89], v[66:67], off offset:48
	global_load_dwordx4 v[70:73], v[66:67], off
	s_nop 0
	global_load_dwordx4 v[66:69], v[66:67], off offset:16
	v_mov_b32_e32 v90, v156
	v_mov_b32_e32 v91, v156
	s_waitcnt vmcnt(3)
	v_mul_f32_e32 v80, v90, v76
	v_mul_f32_e32 v81, v91, v77
	v_mul_f32_e32 v78, v156, v74
	v_mul_f32_e32 v79, v157, v75
	s_waitcnt vmcnt(2)
	v_mul_f32_e32 v74, v90, v88
	v_mul_f32_e32 v75, v91, v89
	v_mul_f32_e32 v76, v156, v86
	v_mul_f32_e32 v77, v157, v87
.LBB0_830:
	s_or_b64 exec, exec, s[4:5]
	s_and_b64 vcc, exec, s[12:13]
	s_cbranch_vccnz .LBB0_832
	v_and_b32_e32 v86, 64, v182
	v_xor_b32_e32 v85, 16, v182
	v_add_u32_e32 v86, 64, v86
	v_cmp_lt_i32_e32 vcc, v85, v86
	s_nop 1
	v_cndmask_b32_e32 v85, v182, v85, vcc
	v_lshlrev_b32_e32 v85, 2, v85
	ds_bpermute_b32 v86, v85, v62
	ds_bpermute_b32 v87, v85, v63
	ds_bpermute_b32 v88, v85, v58
	ds_bpermute_b32 v90, v85, v64
	ds_bpermute_b32 v91, v85, v65
	ds_bpermute_b32 v89, v85, v59
	ds_bpermute_b32 v92, v85, v60
	ds_bpermute_b32 v93, v85, v61
	s_waitcnt lgkmcnt(6)
	v_mul_f32_e32 v86, v78, v86
	v_mul_f32_e32 v87, v79, v87
	s_waitcnt lgkmcnt(3)
	v_mul_f32_e32 v90, v80, v90
	v_mul_f32_e32 v91, v81, v91
	s_waitcnt vmcnt(1)
	v_fma_f32 v62, v62, v70, v86
	v_fma_f32 v63, v63, v71, v87
	s_waitcnt lgkmcnt(2)
	v_mul_f32_e32 v86, v76, v88
	v_mul_f32_e32 v87, v77, v89
	s_waitcnt lgkmcnt(0)
	v_mul_f32_e32 v88, v74, v92
	v_mul_f32_e32 v89, v75, v93
	v_fma_f32 v64, v64, v72, v90
	v_fma_f32 v65, v65, v73, v91
	s_waitcnt vmcnt(0)
	v_fma_f32 v60, v60, v68, v88
	v_fma_f32 v61, v61, v69, v89
	v_fma_f32 v58, v58, v66, v86
	v_fma_f32 v59, v59, v67, v87
.LBB0_832:
	s_waitcnt vmcnt(0)
	v_mul_f32_e32 v84, v185, v84
	v_lshlrev_b64 v[82:83], 8, v[82:83]
	v_lshl_add_u64 v[82:83], v[162:163], 0, v[82:83]
	v_mul_f32_e32 v86, v84, v60
	v_mul_f32_e32 v87, v84, v61
	v_mul_f32_e32 v60, v84, v58
	v_mul_f32_e32 v61, v84, v59
	s_and_b64 vcc, exec, s[12:13]
	v_mul_f32_e32 v64, v84, v64
	v_mul_f32_e32 v65, v84, v65
	v_mul_f32_e32 v62, v84, v62
	v_mul_f32_e32 v63, v84, v63
	v_cvt_pk_bf16_f32 v58, v62, v63
	v_cvt_pk_bf16_f32 v59, v64, v65
	v_cvt_pk_bf16_f32 v60, v60, v61
	v_cvt_pk_bf16_f32 v61, v86, v87
	global_store_dwordx4 v[82:83], v[58:61], off
	s_cbranch_vccnz .LBB0_834
	s_nop 0
	v_and_b32_e32 v59, 64, v182
	v_xor_b32_e32 v58, 16, v182
	v_add_u32_e32 v59, 64, v59
	v_cmp_lt_i32_e32 vcc, v58, v59
	s_nop 1
	v_cndmask_b32_e32 v58, v182, v58, vcc
	v_lshlrev_b32_e32 v65, 2, v58
	ds_bpermute_b32 v58, v65, v54
	ds_bpermute_b32 v59, v65, v55
	ds_bpermute_b32 v60, v65, v50
	ds_bpermute_b32 v62, v65, v56
	ds_bpermute_b32 v63, v65, v57
	ds_bpermute_b32 v61, v65, v51
	ds_bpermute_b32 v64, v65, v52
	ds_bpermute_b32 v65, v65, v53
	s_waitcnt lgkmcnt(6)
	v_mul_f32_e32 v58, v78, v58
	v_mul_f32_e32 v59, v79, v59
	s_waitcnt lgkmcnt(3)
	v_mul_f32_e32 v62, v80, v62
	v_mul_f32_e32 v63, v81, v63
	v_fma_f32 v54, v54, v70, v58
	v_fma_f32 v55, v55, v71, v59
	s_waitcnt lgkmcnt(2)
	v_mul_f32_e32 v58, v76, v60
	v_mul_f32_e32 v59, v77, v61
	s_waitcnt lgkmcnt(0)
	v_mul_f32_e32 v60, v74, v64
	v_mul_f32_e32 v61, v75, v65
	v_fma_f32 v56, v56, v72, v62
	v_fma_f32 v57, v57, v73, v63
	v_fma_f32 v52, v52, v68, v60
	v_fma_f32 v53, v53, v69, v61
	v_fma_f32 v50, v50, v66, v58
	v_fma_f32 v51, v51, v67, v59
.LBB0_834:
	v_mov_b32_e32 v85, v84
	v_mov_b32_e32 v58, v84
	v_mov_b32_e32 v59, v84
	v_mul_f32_e32 v54, v84, v54
	v_mul_f32_e32 v55, v85, v55
	v_mul_f32_e32 v56, v58, v56
	v_mul_f32_e32 v57, v59, v57
	v_mul_f32_e32 v58, v58, v52
	v_mul_f32_e32 v59, v59, v53
	v_mul_f32_e32 v52, v84, v50
	v_mul_f32_e32 v53, v85, v51
	v_cvt_pk_bf16_f32 v50, v54, v55
	v_add_co_u32_e32 v54, vcc, s44, v82
	v_cvt_pk_bf16_f32 v51, v56, v57
	v_cvt_pk_bf16_f32 v52, v52, v53
	v_cvt_pk_bf16_f32 v53, v58, v59
	v_add_u32_e32 v66, 0x90, v158
	s_nop 0
	v_addc_co_u32_e32 v55, vcc, 0, v83, vcc
	global_store_dwordx4 v[54:55], v[50:53], off
	global_load_dword v68, v[160:161], off offset:576
	v_ashrrev_i32_e32 v67, 31, v66
	v_mov_b32_e32 v62, 0
	v_mov_b32_e32 v54, 1.0
	v_mov_b32_e32 v55, 1.0
	v_mov_b32_e32 v56, 1.0
	v_mov_b32_e32 v57, 1.0
	v_mov_b32_e32 v50, 1.0
	v_mov_b32_e32 v51, 1.0
	v_mov_b32_e32 v52, 1.0
	v_mov_b32_e32 v53, 1.0
	v_mov_b32_e32 v63, 0
	v_mov_b32_e32 v64, 0
	v_mov_b32_e32 v65, 0
	v_mov_b32_e32 v60, 0
	v_mov_b32_e32 v61, 0
	v_mov_b32_e32 v58, 0
	v_mov_b32_e32 v59, 0
	s_and_saveexec_b64 s[4:5], s[2:3]
	s_cbranch_execz .LBB0_836
	v_lshlrev_b64 v[50:51], 6, v[66:67]
	v_lshl_add_u64 v[50:51], s[14:15], 0, v[50:51]
	global_load_dwordx4 v[58:61], v[50:51], off offset:32
	global_load_dwordx4 v[70:73], v[50:51], off offset:48
	global_load_dwordx4 v[54:57], v[50:51], off
	s_nop 0
	global_load_dwordx4 v[50:53], v[50:51], off offset:16
	v_mov_b32_e32 v74, v156
	v_mov_b32_e32 v75, v156
	s_waitcnt vmcnt(3)
	v_mul_f32_e32 v64, v74, v60
	v_mul_f32_e32 v65, v75, v61
	v_mul_f32_e32 v62, v156, v58
	v_mul_f32_e32 v63, v157, v59
	s_waitcnt vmcnt(2)
	v_mul_f32_e32 v58, v74, v72
	v_mul_f32_e32 v59, v75, v73
	v_mul_f32_e32 v60, v156, v70
	v_mul_f32_e32 v61, v157, v71
.LBB0_836:
	s_or_b64 exec, exec, s[4:5]
	s_and_b64 vcc, exec, s[12:13]
	s_cbranch_vccnz .LBB0_838
	v_and_b32_e32 v70, 64, v182
	v_xor_b32_e32 v69, 16, v182
	v_add_u32_e32 v70, 64, v70
	v_cmp_lt_i32_e32 vcc, v69, v70
	s_nop 1
	v_cndmask_b32_e32 v69, v182, v69, vcc
	v_lshlrev_b32_e32 v69, 2, v69
	ds_bpermute_b32 v70, v69, v46
	ds_bpermute_b32 v71, v69, v47
	ds_bpermute_b32 v72, v69, v42
	ds_bpermute_b32 v74, v69, v48
	ds_bpermute_b32 v75, v69, v49
	ds_bpermute_b32 v73, v69, v43
	ds_bpermute_b32 v76, v69, v44
	ds_bpermute_b32 v77, v69, v45
	s_waitcnt lgkmcnt(6)
	v_mul_f32_e32 v70, v62, v70
	v_mul_f32_e32 v71, v63, v71
	s_waitcnt lgkmcnt(3)
	v_mul_f32_e32 v74, v64, v74
	v_mul_f32_e32 v75, v65, v75
	s_waitcnt vmcnt(1)
	v_fma_f32 v46, v46, v54, v70
	v_fma_f32 v47, v47, v55, v71
	s_waitcnt lgkmcnt(2)
	v_mul_f32_e32 v70, v60, v72
	v_mul_f32_e32 v71, v61, v73
	s_waitcnt lgkmcnt(0)
	v_mul_f32_e32 v72, v58, v76
	v_mul_f32_e32 v73, v59, v77
	v_fma_f32 v48, v48, v56, v74
	v_fma_f32 v49, v49, v57, v75
	s_waitcnt vmcnt(0)
	v_fma_f32 v44, v44, v52, v72
	v_fma_f32 v45, v45, v53, v73
	v_fma_f32 v42, v42, v50, v70
	v_fma_f32 v43, v43, v51, v71
.LBB0_838:
	s_waitcnt vmcnt(0)
	v_mul_f32_e32 v68, v185, v68
	v_lshlrev_b64 v[66:67], 8, v[66:67]
	v_lshl_add_u64 v[66:67], v[162:163], 0, v[66:67]
	v_mul_f32_e32 v70, v68, v44
	v_mul_f32_e32 v71, v68, v45
	v_mul_f32_e32 v44, v68, v42
	v_mul_f32_e32 v45, v68, v43
	s_and_b64 vcc, exec, s[12:13]
	v_mul_f32_e32 v48, v68, v48
	v_mul_f32_e32 v49, v68, v49
	v_mul_f32_e32 v46, v68, v46
	v_mul_f32_e32 v47, v68, v47
	v_cvt_pk_bf16_f32 v42, v46, v47
	v_cvt_pk_bf16_f32 v43, v48, v49
	v_cvt_pk_bf16_f32 v44, v44, v45
	v_cvt_pk_bf16_f32 v45, v70, v71
	global_store_dwordx4 v[66:67], v[42:45], off
	s_cbranch_vccnz .LBB0_840
	s_nop 0
	v_and_b32_e32 v43, 64, v182
	v_xor_b32_e32 v42, 16, v182
	v_add_u32_e32 v43, 64, v43
	v_cmp_lt_i32_e32 vcc, v42, v43
	s_nop 1
	v_cndmask_b32_e32 v42, v182, v42, vcc
	v_lshlrev_b32_e32 v49, 2, v42
	ds_bpermute_b32 v42, v49, v38
	ds_bpermute_b32 v43, v49, v39
	ds_bpermute_b32 v44, v49, v34
	ds_bpermute_b32 v46, v49, v40
	ds_bpermute_b32 v47, v49, v41
	ds_bpermute_b32 v45, v49, v35
	ds_bpermute_b32 v48, v49, v36
	ds_bpermute_b32 v49, v49, v37
	s_waitcnt lgkmcnt(6)
	v_mul_f32_e32 v42, v62, v42
	v_mul_f32_e32 v43, v63, v43
	s_waitcnt lgkmcnt(3)
	v_mul_f32_e32 v46, v64, v46
	v_mul_f32_e32 v47, v65, v47
	v_fma_f32 v38, v38, v54, v42
	v_fma_f32 v39, v39, v55, v43
	s_waitcnt lgkmcnt(2)
	v_mul_f32_e32 v42, v60, v44
	v_mul_f32_e32 v43, v61, v45
	s_waitcnt lgkmcnt(0)
	v_mul_f32_e32 v44, v58, v48
	v_mul_f32_e32 v45, v59, v49
	v_fma_f32 v40, v40, v56, v46
	v_fma_f32 v41, v41, v57, v47
	v_fma_f32 v36, v36, v52, v44
	v_fma_f32 v37, v37, v53, v45
	v_fma_f32 v34, v34, v50, v42
	v_fma_f32 v35, v35, v51, v43
.LBB0_840:
	v_mov_b32_e32 v69, v68
	v_mov_b32_e32 v42, v68
	v_mov_b32_e32 v43, v68
	v_mul_f32_e32 v38, v68, v38
	v_mul_f32_e32 v39, v69, v39
	v_mul_f32_e32 v40, v42, v40
	v_mul_f32_e32 v41, v43, v41
	v_mul_f32_e32 v42, v42, v36
	v_mul_f32_e32 v43, v43, v37
	v_mul_f32_e32 v36, v68, v34
	v_mul_f32_e32 v37, v69, v35
	v_cvt_pk_bf16_f32 v34, v38, v39
	v_add_co_u32_e32 v38, vcc, s44, v66
	v_cvt_pk_bf16_f32 v35, v40, v41
	v_cvt_pk_bf16_f32 v36, v36, v37
	v_cvt_pk_bf16_f32 v37, v42, v43
	v_add_u32_e32 v50, 0xa0, v158
	s_nop 0
	v_addc_co_u32_e32 v39, vcc, 0, v67, vcc
	global_store_dwordx4 v[38:39], v[34:37], off
	global_load_dword v52, v[160:161], off offset:640
	v_ashrrev_i32_e32 v51, 31, v50
	v_mov_b32_e32 v46, 0
	v_mov_b32_e32 v38, 1.0
	v_mov_b32_e32 v39, 1.0
	v_mov_b32_e32 v40, 1.0
	v_mov_b32_e32 v41, 1.0
	v_mov_b32_e32 v34, 1.0
	v_mov_b32_e32 v35, 1.0
	v_mov_b32_e32 v36, 1.0
	v_mov_b32_e32 v37, 1.0
	v_mov_b32_e32 v47, 0
	v_mov_b32_e32 v48, 0
	v_mov_b32_e32 v49, 0
	v_mov_b32_e32 v44, 0
	v_mov_b32_e32 v45, 0
	v_mov_b32_e32 v42, 0
	v_mov_b32_e32 v43, 0
	s_and_saveexec_b64 s[4:5], s[2:3]
	s_cbranch_execz .LBB0_842
	v_lshlrev_b64 v[34:35], 6, v[50:51]
	v_lshl_add_u64 v[34:35], s[14:15], 0, v[34:35]
	global_load_dwordx4 v[42:45], v[34:35], off offset:32
	global_load_dwordx4 v[54:57], v[34:35], off offset:48
	global_load_dwordx4 v[38:41], v[34:35], off
	s_nop 0
	global_load_dwordx4 v[34:37], v[34:35], off offset:16
	v_mov_b32_e32 v58, v156
	v_mov_b32_e32 v59, v156
	s_waitcnt vmcnt(3)
	v_mul_f32_e32 v48, v58, v44
	v_mul_f32_e32 v49, v59, v45
	v_mul_f32_e32 v46, v156, v42
	v_mul_f32_e32 v47, v157, v43
	s_waitcnt vmcnt(2)
	v_mul_f32_e32 v42, v58, v56
	v_mul_f32_e32 v43, v59, v57
	v_mul_f32_e32 v44, v156, v54
	v_mul_f32_e32 v45, v157, v55
.LBB0_842:
	s_or_b64 exec, exec, s[4:5]
	s_and_b64 vcc, exec, s[12:13]
	s_cbranch_vccnz .LBB0_844
	v_and_b32_e32 v54, 64, v182
	v_xor_b32_e32 v53, 16, v182
	v_add_u32_e32 v54, 64, v54
	v_cmp_lt_i32_e32 vcc, v53, v54
	s_nop 1
	v_cndmask_b32_e32 v53, v182, v53, vcc
	v_lshlrev_b32_e32 v53, 2, v53
	ds_bpermute_b32 v54, v53, v30
	ds_bpermute_b32 v55, v53, v31
	ds_bpermute_b32 v56, v53, v26
	ds_bpermute_b32 v58, v53, v32
	ds_bpermute_b32 v59, v53, v33
	ds_bpermute_b32 v57, v53, v27
	ds_bpermute_b32 v60, v53, v28
	ds_bpermute_b32 v61, v53, v29
	s_waitcnt lgkmcnt(6)
	v_mul_f32_e32 v54, v46, v54
	v_mul_f32_e32 v55, v47, v55
	s_waitcnt lgkmcnt(3)
	v_mul_f32_e32 v58, v48, v58
	v_mul_f32_e32 v59, v49, v59
	s_waitcnt vmcnt(1)
	v_fma_f32 v30, v30, v38, v54
	v_fma_f32 v31, v31, v39, v55
	s_waitcnt lgkmcnt(2)
	v_mul_f32_e32 v54, v44, v56
	v_mul_f32_e32 v55, v45, v57
	s_waitcnt lgkmcnt(0)
	v_mul_f32_e32 v56, v42, v60
	v_mul_f32_e32 v57, v43, v61
	v_fma_f32 v32, v32, v40, v58
	v_fma_f32 v33, v33, v41, v59
	s_waitcnt vmcnt(0)
	v_fma_f32 v28, v28, v36, v56
	v_fma_f32 v29, v29, v37, v57
	v_fma_f32 v26, v26, v34, v54
	v_fma_f32 v27, v27, v35, v55
.LBB0_844:
	s_waitcnt vmcnt(0)
	v_mul_f32_e32 v52, v185, v52
	v_lshlrev_b64 v[50:51], 8, v[50:51]
	v_lshl_add_u64 v[50:51], v[162:163], 0, v[50:51]
	v_mul_f32_e32 v54, v52, v28
	v_mul_f32_e32 v55, v52, v29
	v_mul_f32_e32 v28, v52, v26
	v_mul_f32_e32 v29, v52, v27
	s_and_b64 vcc, exec, s[12:13]
	v_mul_f32_e32 v32, v52, v32
	v_mul_f32_e32 v33, v52, v33
	v_mul_f32_e32 v30, v52, v30
	v_mul_f32_e32 v31, v52, v31
	v_cvt_pk_bf16_f32 v26, v30, v31
	v_cvt_pk_bf16_f32 v27, v32, v33
	v_cvt_pk_bf16_f32 v28, v28, v29
	v_cvt_pk_bf16_f32 v29, v54, v55
	global_store_dwordx4 v[50:51], v[26:29], off
	s_cbranch_vccnz .LBB0_846
	s_nop 0
	v_and_b32_e32 v27, 64, v182
	v_xor_b32_e32 v26, 16, v182
	v_add_u32_e32 v27, 64, v27
	v_cmp_lt_i32_e32 vcc, v26, v27
	s_nop 1
	v_cndmask_b32_e32 v26, v182, v26, vcc
	v_lshlrev_b32_e32 v33, 2, v26
	ds_bpermute_b32 v26, v33, v22
	ds_bpermute_b32 v27, v33, v23
	ds_bpermute_b32 v28, v33, v18
	ds_bpermute_b32 v30, v33, v24
	ds_bpermute_b32 v31, v33, v25
	ds_bpermute_b32 v29, v33, v19
	ds_bpermute_b32 v32, v33, v20
	ds_bpermute_b32 v33, v33, v21
	s_waitcnt lgkmcnt(6)
	v_mul_f32_e32 v26, v46, v26
	v_mul_f32_e32 v27, v47, v27
	s_waitcnt lgkmcnt(3)
	v_mul_f32_e32 v30, v48, v30
	v_mul_f32_e32 v31, v49, v31
	v_fma_f32 v22, v22, v38, v26
	v_fma_f32 v23, v23, v39, v27
	s_waitcnt lgkmcnt(2)
	v_mul_f32_e32 v26, v44, v28
	v_mul_f32_e32 v27, v45, v29
	s_waitcnt lgkmcnt(0)
	v_mul_f32_e32 v28, v42, v32
	v_mul_f32_e32 v29, v43, v33
	v_fma_f32 v24, v24, v40, v30
	v_fma_f32 v25, v25, v41, v31
	v_fma_f32 v20, v20, v36, v28
	v_fma_f32 v21, v21, v37, v29
	v_fma_f32 v18, v18, v34, v26
	v_fma_f32 v19, v19, v35, v27
.LBB0_846:
	v_mov_b32_e32 v53, v52
	v_mov_b32_e32 v26, v52
	v_mov_b32_e32 v27, v52
	v_mul_f32_e32 v22, v52, v22
	v_mul_f32_e32 v23, v53, v23
	v_mul_f32_e32 v24, v26, v24
	v_mul_f32_e32 v25, v27, v25
	v_mul_f32_e32 v26, v26, v20
	v_mul_f32_e32 v27, v27, v21
	v_mul_f32_e32 v20, v52, v18
	v_mul_f32_e32 v21, v53, v19
	v_cvt_pk_bf16_f32 v18, v22, v23
	v_add_co_u32_e32 v22, vcc, s44, v50
	v_cvt_pk_bf16_f32 v19, v24, v25
	v_cvt_pk_bf16_f32 v20, v20, v21
	v_cvt_pk_bf16_f32 v21, v26, v27
	v_add_u32_e32 v34, 0xb0, v158
	s_nop 0
	v_addc_co_u32_e32 v23, vcc, 0, v51, vcc
	global_store_dwordx4 v[22:23], v[18:21], off
	global_load_dword v36, v[160:161], off offset:704
	v_ashrrev_i32_e32 v35, 31, v34
	v_mov_b32_e32 v30, 0
	v_mov_b32_e32 v22, 1.0
	v_mov_b32_e32 v23, 1.0
	v_mov_b32_e32 v24, 1.0
	v_mov_b32_e32 v25, 1.0
	v_mov_b32_e32 v18, 1.0
	v_mov_b32_e32 v19, 1.0
	v_mov_b32_e32 v20, 1.0
	v_mov_b32_e32 v21, 1.0
	v_mov_b32_e32 v31, 0
	v_mov_b32_e32 v32, 0
	v_mov_b32_e32 v33, 0
	v_mov_b32_e32 v28, 0
	v_mov_b32_e32 v29, 0
	v_mov_b32_e32 v26, 0
	v_mov_b32_e32 v27, 0
	s_and_saveexec_b64 s[4:5], s[2:3]
	s_cbranch_execz .LBB0_848
	v_lshlrev_b64 v[18:19], 6, v[34:35]
	v_lshl_add_u64 v[18:19], s[14:15], 0, v[18:19]
	global_load_dwordx4 v[26:29], v[18:19], off offset:32
	global_load_dwordx4 v[38:41], v[18:19], off offset:48
	global_load_dwordx4 v[22:25], v[18:19], off
	s_nop 0
	global_load_dwordx4 v[18:21], v[18:19], off offset:16
	v_mov_b32_e32 v42, v156
	v_mov_b32_e32 v43, v156
	s_waitcnt vmcnt(3)
	v_mul_f32_e32 v32, v42, v28
	v_mul_f32_e32 v33, v43, v29
	v_mul_f32_e32 v30, v156, v26
	v_mul_f32_e32 v31, v157, v27
	s_waitcnt vmcnt(2)
	v_mul_f32_e32 v26, v42, v40
	v_mul_f32_e32 v27, v43, v41
	v_mul_f32_e32 v28, v156, v38
	v_mul_f32_e32 v29, v157, v39
.LBB0_848:
	s_or_b64 exec, exec, s[4:5]
	s_and_b64 vcc, exec, s[12:13]
	s_cbranch_vccnz .LBB0_850
	v_and_b32_e32 v38, 64, v182
	v_xor_b32_e32 v37, 16, v182
	v_add_u32_e32 v38, 64, v38
	v_cmp_lt_i32_e32 vcc, v37, v38
	s_nop 1
	v_cndmask_b32_e32 v37, v182, v37, vcc
	v_lshlrev_b32_e32 v37, 2, v37
	ds_bpermute_b32 v38, v37, v14
	ds_bpermute_b32 v39, v37, v15
	ds_bpermute_b32 v40, v37, v10
	ds_bpermute_b32 v42, v37, v16
	ds_bpermute_b32 v43, v37, v17
	ds_bpermute_b32 v41, v37, v11
	ds_bpermute_b32 v44, v37, v12
	ds_bpermute_b32 v45, v37, v13
	s_waitcnt lgkmcnt(6)
	v_mul_f32_e32 v38, v30, v38
	v_mul_f32_e32 v39, v31, v39
	s_waitcnt lgkmcnt(3)
	v_mul_f32_e32 v42, v32, v42
	v_mul_f32_e32 v43, v33, v43
	s_waitcnt vmcnt(1)
	v_fma_f32 v14, v14, v22, v38
	v_fma_f32 v15, v15, v23, v39
	s_waitcnt lgkmcnt(2)
	v_mul_f32_e32 v38, v28, v40
	v_mul_f32_e32 v39, v29, v41
	s_waitcnt lgkmcnt(0)
	v_mul_f32_e32 v40, v26, v44
	v_mul_f32_e32 v41, v27, v45
	v_fma_f32 v16, v16, v24, v42
	v_fma_f32 v17, v17, v25, v43
	s_waitcnt vmcnt(0)
	v_fma_f32 v12, v12, v20, v40
	v_fma_f32 v13, v13, v21, v41
	v_fma_f32 v10, v10, v18, v38
	v_fma_f32 v11, v11, v19, v39
.LBB0_850:
	s_waitcnt vmcnt(0)
	v_mul_f32_e32 v36, v185, v36
	v_lshlrev_b64 v[34:35], 8, v[34:35]
	v_lshl_add_u64 v[34:35], v[162:163], 0, v[34:35]
	v_mul_f32_e32 v38, v36, v12
	v_mul_f32_e32 v39, v36, v13
	v_mul_f32_e32 v12, v36, v10
	v_mul_f32_e32 v13, v36, v11
	s_and_b64 vcc, exec, s[12:13]
	v_mul_f32_e32 v16, v36, v16
	v_mul_f32_e32 v17, v36, v17
	v_mul_f32_e32 v14, v36, v14
	v_mul_f32_e32 v15, v36, v15
	v_cvt_pk_bf16_f32 v10, v14, v15
	v_cvt_pk_bf16_f32 v11, v16, v17
	v_cvt_pk_bf16_f32 v12, v12, v13
	v_cvt_pk_bf16_f32 v13, v38, v39
	global_store_dwordx4 v[34:35], v[10:13], off
	s_cbranch_vccnz .LBB0_852
	s_nop 0
	v_and_b32_e32 v11, 64, v182
	v_xor_b32_e32 v10, 16, v182
	v_add_u32_e32 v11, 64, v11
	v_cmp_lt_i32_e32 vcc, v10, v11
	s_nop 1
	v_cndmask_b32_e32 v10, v182, v10, vcc
	v_lshlrev_b32_e32 v17, 2, v10
	ds_bpermute_b32 v10, v17, v6
	ds_bpermute_b32 v11, v17, v7
	ds_bpermute_b32 v12, v17, v2
	ds_bpermute_b32 v14, v17, v8
	ds_bpermute_b32 v15, v17, v9
	ds_bpermute_b32 v13, v17, v3
	ds_bpermute_b32 v16, v17, v4
	ds_bpermute_b32 v17, v17, v5
	s_waitcnt lgkmcnt(6)
	v_mul_f32_e32 v10, v30, v10
	v_mul_f32_e32 v11, v31, v11
	s_waitcnt lgkmcnt(3)
	v_mul_f32_e32 v14, v32, v14
	v_mul_f32_e32 v15, v33, v15
	v_fma_f32 v6, v6, v22, v10
	v_fma_f32 v7, v7, v23, v11
	s_waitcnt lgkmcnt(2)
	v_mul_f32_e32 v10, v28, v12
	v_mul_f32_e32 v11, v29, v13
	s_waitcnt lgkmcnt(0)
	v_mul_f32_e32 v12, v26, v16
	v_mul_f32_e32 v13, v27, v17
	v_fma_f32 v8, v8, v24, v14
	v_fma_f32 v9, v9, v25, v15
	v_fma_f32 v4, v4, v20, v12
	v_fma_f32 v5, v5, v21, v13
	v_fma_f32 v2, v2, v18, v10
	v_fma_f32 v3, v3, v19, v11
.LBB0_852:
	v_mov_b32_e32 v37, v36
	v_mov_b32_e32 v10, v36
	v_mov_b32_e32 v11, v36
	v_mul_f32_e32 v6, v36, v6
	v_mul_f32_e32 v7, v37, v7
	v_mul_f32_e32 v8, v10, v8
	v_mul_f32_e32 v9, v11, v9
	v_mul_f32_e32 v10, v10, v4
	v_mul_f32_e32 v11, v11, v5
	v_mul_f32_e32 v4, v36, v2
	v_mul_f32_e32 v5, v37, v3
	v_cvt_pk_bf16_f32 v2, v6, v7
	v_add_co_u32_e32 v6, vcc, 0x200000, v34
	v_cvt_pk_bf16_f32 v3, v8, v9
	v_cvt_pk_bf16_f32 v4, v4, v5
	v_cvt_pk_bf16_f32 v5, v10, v11
	s_mov_b64 s[2:3], -1
	s_nop 0
	v_addc_co_u32_e32 v7, vcc, 0, v35, vcc
	global_store_dwordx4 v[6:7], v[2:5], off
	s_andn2_b64 vcc, exec, s[10:11]
	s_cbranch_vccnz .LBB0_797
	s_andn2_b64 vcc, exec, s[6:7]
	s_cbranch_vccnz .LBB0_796
	s_barrier
	s_branch .LBB0_796

.LBB0_2483:
	v_mul_f32_e32 v6, s12, v158
	v_mul_f32_e32 v7, s12, v159
	v_mov_b32_e32 v2, v180
	v_mul_f32_e32 v16, 0xbfb8aa3b, v6
	v_exp_f32_e32 v18, v16
	v_mul_f32_e32 v16, 0xbfb8aa3b, v7
	v_exp_f32_e32 v19, v16
	s_nop 15
	s_nop 15
	v_add_f32_e32 v18, 1.0, v18
	v_rcp_f32_e32 v20, v18
	v_add_f32_e32 v18, 1.0, v19
	v_rcp_f32_e32 v21, v18
	v_mul_f32_e32 v14, s12, v150
	v_mul_f32_e32 v15, s12, v151
	v_lshrrev_b32_e32 v3, 1, v2
	v_and_or_b32 v2, v2, 15, s39
	v_mul_f32_e32 v6, v6, v20
	v_and_b32_e32 v170, 24, v3
	v_lshl_add_u32 v4, s4, 8, v2
	v_mul_f32_e32 v2, s12, v160
	v_mul_f32_e32 v3, s12, v161
	v_mul_f32_e32 v14, v6, v14
	v_mul_f32_e32 v6, v7, v21
	v_mul_f32_e32 v7, v6, v15
	v_mul_f32_e32 v6, 0xbfb8aa3b, v2
	v_exp_f32_e32 v15, v6
	v_mul_f32_e32 v6, 0xbfb8aa3b, v3
	v_mul_f32_e32 v10, s12, v154
	v_mul_f32_e32 v11, s12, v155
	v_exp_f32_e32 v20, v6
	v_add_f32_e32 v15, 1.0, v15
	v_rcp_f32_e32 v15, v15
	v_mov_b32_e32 v6, v171
	v_cvt_pk_fp8_f32 v6, v14, v7
	v_mul_f32_e32 v7, 0xbfb8aa3b, v10
	v_mul_f32_e32 v12, s12, v152
	v_mul_f32_e32 v13, s12, v153
	v_mul_f32_e32 v2, v2, v15
	v_exp_f32_e32 v7, v7
	v_mul_f32_e32 v2, v2, v12
	v_mul_f32_e32 v12, 0xbfb8aa3b, v11
	v_add_f32_e32 v20, 1.0, v20
	v_exp_f32_e32 v12, v12
	v_rcp_f32_e32 v20, v20
	v_add_f32_e32 v7, 1.0, v7
	v_rcp_f32_e32 v7, v7
	v_add_f32_e32 v12, 1.0, v12
	v_mul_f32_e32 v3, v3, v20
	v_rcp_f32_e32 v12, v12
	v_mul_f32_e32 v8, s12, v156
	v_mul_f32_e32 v9, s12, v157
	v_mul_f32_e32 v3, v3, v13
	v_cvt_pk_fp8_f32 v6, v2, v3 op_sel:[0,0,1]
	v_mul_f32_e32 v2, v10, v7
	v_mul_f32_e32 v7, 0xbfb8aa3b, v8
	v_exp_f32_e32 v10, v7
	v_mul_f32_e32 v7, 0xbfb8aa3b, v9
	v_mul_f32_e32 v3, v11, v12
	v_exp_f32_e32 v11, v7
	v_add_f32_e32 v10, 1.0, v10
	v_mul_f32_e32 v18, s12, v146
	v_mul_f32_e32 v19, s12, v147
	v_rcp_f32_e32 v10, v10
	v_add_f32_e32 v11, 1.0, v11
	v_rcp_f32_e32 v11, v11
	v_mul_f32_e32 v2, v2, v18
	v_mul_f32_e32 v3, v3, v19
	v_mov_b32_e32 v7, v171
	v_cvt_pk_fp8_f32 v7, v2, v3
	v_mul_f32_e32 v16, s12, v148
	v_mul_f32_e32 v17, s12, v149
	v_mul_f32_e32 v2, v8, v10
	v_mul_f32_e32 v3, v9, v11
	v_ashrrev_i32_e32 v5, 31, v4
	v_mul_f32_e32 v2, v2, v16
	v_mul_f32_e32 v3, v3, v17
	v_mul_f32_e32 v10, s12, v142
	v_mul_f32_e32 v11, s12, v143
	v_cvt_pk_fp8_f32 v7, v2, v3 op_sel:[0,0,1]
	v_lshlrev_b64 v[2:3], 7, v[4:5]
	v_mul_f32_e32 v5, 0xbfb8aa3b, v10
	v_mul_f32_e32 v20, 0xbfb8aa3b, v11
	v_exp_f32_e32 v5, v5
	v_exp_f32_e32 v22, v20
	v_mul_f32_e32 v8, s12, v144
	v_mul_f32_e32 v9, s12, v145
	v_mul_f32_e32 v18, s12, v134
	v_mul_f32_e32 v19, s12, v135
	v_add_f32_e32 v5, 1.0, v5
	v_add_f32_e32 v22, 1.0, v22
	v_rcp_f32_e32 v5, v5
	v_rcp_f32_e32 v24, v22
	v_mul_f32_e32 v14, s12, v138
	v_mul_f32_e32 v15, s12, v139
	v_mul_f32_e32 v16, s12, v136
	v_mul_f32_e32 v17, s12, v137
	v_mul_f32_e32 v5, v10, v5
	v_mul_f32_e32 v10, v11, v24
	v_mul_f32_e32 v11, v10, v19
	v_mul_f32_e32 v10, 0xbfb8aa3b, v8
	v_mul_f32_e32 v5, v5, v18
	v_exp_f32_e32 v18, v10
	v_mul_f32_e32 v10, 0xbfb8aa3b, v9
	v_exp_f32_e32 v19, v10
	v_mov_b32_e32 v10, v171
	v_add_f32_e32 v18, 1.0, v18
	v_rcp_f32_e32 v18, v18
	v_add_f32_e32 v19, 1.0, v19
	v_rcp_f32_e32 v19, v19
	v_cvt_pk_fp8_f32 v10, v5, v11
	v_mul_f32_e32 v5, v8, v18
	v_mul_f32_e32 v11, 0xbfb8aa3b, v15
	v_mul_f32_e32 v8, v9, v19
	v_mul_f32_e32 v9, 0xbfb8aa3b, v14
	v_exp_f32_e32 v9, v9
	v_exp_f32_e32 v11, v11
	v_mul_f32_e32 v12, s12, v140
	v_mul_f32_e32 v13, s12, v141
	v_mul_f32_e32 v5, v5, v16
	v_add_f32_e32 v9, 1.0, v9
	v_add_f32_e32 v11, 1.0, v11
	v_rcp_f32_e32 v9, v9
	v_rcp_f32_e32 v11, v11
	v_mul_f32_e32 v8, v8, v17
	v_cvt_pk_fp8_f32 v10, v5, v8 op_sel:[0,0,1]
	v_mul_f32_e32 v5, v14, v9
	v_mul_f32_e32 v8, v15, v11
	v_mul_f32_e32 v9, 0xbfb8aa3b, v12
	v_mul_f32_e32 v11, 0xbfb8aa3b, v13
	v_exp_f32_e32 v9, v9
	v_exp_f32_e32 v14, v11
	s_ashr_i32 s23, s22, 31
	s_lshl_b64 s[4:5], s[22:23], 20
	v_readlane_b32 s22, v245, 14
	v_readlane_b32 s23, v245, 15
	s_add_u32 s4, s22, s4
	v_add_f32_e32 v9, 1.0, v9
	v_add_f32_e32 v14, 1.0, v14
	s_addc_u32 s5, s23, s5
	v_mul_f32_e32 v22, s12, v130
	v_mul_f32_e32 v23, s12, v131
	v_rcp_f32_e32 v9, v9
	v_rcp_f32_e32 v14, v14
	v_lshl_add_u64 v[2:3], s[4:5], 0, v[2:3]
	v_mul_f32_e32 v5, v5, v22
	v_mul_f32_e32 v8, v8, v23
	v_mov_b32_e32 v11, v171
	v_lshl_add_u64 v[2:3], v[2:3], 0, s[2:3]
	v_cvt_pk_fp8_f32 v11, v5, v8
	v_lshl_add_u64 v[2:3], v[2:3], 0, v[170:171]
	global_store_dwordx2 v[2:3], v[6:7], off
	v_or_b32_e32 v6, 16, v4
	v_mul_f32_e32 v20, s12, v132
	v_mul_f32_e32 v21, s12, v133
	v_mul_f32_e32 v5, v12, v9
	v_mul_f32_e32 v8, v13, v14
	v_ashrrev_i32_e32 v7, 31, v6
	v_mul_f32_e32 v5, v5, v20
	v_mul_f32_e32 v8, v8, v21
	v_cvt_pk_fp8_f32 v11, v5, v8 op_sel:[0,0,1]
	v_lshlrev_b64 v[6:7], 7, v[6:7]
	v_lshl_add_u64 v[6:7], s[4:5], 0, v[6:7]
	v_lshl_add_u64 v[6:7], v[6:7], 0, s[2:3]
	v_lshl_add_u64 v[6:7], v[6:7], 0, v[170:171]
	global_store_dwordx2 v[6:7], v[10:11], off
	v_mul_f32_e32 v10, s12, v126
	v_mul_f32_e32 v11, s12, v127
	v_mul_f32_e32 v8, s12, v128
	v_mul_f32_e32 v9, s12, v129
	v_mul_f32_e32 v5, 0xbfb8aa3b, v10
	v_mul_f32_e32 v20, 0xbfb8aa3b, v11
	v_exp_f32_e32 v5, v5
	v_exp_f32_e32 v22, v20
	v_mul_f32_e32 v18, s12, v118
	v_mul_f32_e32 v19, s12, v119
	v_mul_f32_e32 v14, s12, v122
	v_mul_f32_e32 v15, s12, v123
	v_add_f32_e32 v5, 1.0, v5
	v_add_f32_e32 v22, 1.0, v22
	v_rcp_f32_e32 v5, v5
	v_rcp_f32_e32 v24, v22
	v_mul_f32_e32 v16, s12, v120
	v_mul_f32_e32 v17, s12, v121
	v_mul_f32_e32 v12, s12, v124
	v_mul_f32_e32 v13, s12, v125
	v_mul_f32_e32 v5, v10, v5
	v_mul_f32_e32 v10, v11, v24
	v_mul_f32_e32 v11, v10, v19
	v_mul_f32_e32 v10, 0xbfb8aa3b, v8
	v_mul_f32_e32 v5, v5, v18
	v_exp_f32_e32 v18, v10
	v_mul_f32_e32 v10, 0xbfb8aa3b, v9
	v_exp_f32_e32 v19, v10
	v_mov_b32_e32 v10, v171
	v_add_f32_e32 v18, 1.0, v18
	v_rcp_f32_e32 v18, v18
	v_add_f32_e32 v19, 1.0, v19
	v_rcp_f32_e32 v19, v19
	v_cvt_pk_fp8_f32 v10, v5, v11
	v_mul_f32_e32 v5, v8, v18
	v_mul_f32_e32 v11, 0xbfb8aa3b, v15
	v_mul_f32_e32 v8, v9, v19
	v_mul_f32_e32 v9, 0xbfb8aa3b, v14
	v_exp_f32_e32 v9, v9
	v_exp_f32_e32 v11, v11
	v_mul_f32_e32 v5, v5, v16
	v_mul_f32_e32 v8, v8, v17
	v_add_f32_e32 v9, 1.0, v9
	v_add_f32_e32 v11, 1.0, v11
	v_rcp_f32_e32 v9, v9
	v_rcp_f32_e32 v11, v11
	v_cvt_pk_fp8_f32 v10, v5, v8 op_sel:[0,0,1]
	v_mul_f32_e32 v22, s12, v114
	v_mul_f32_e32 v23, s12, v115
	v_mul_f32_e32 v5, v14, v9
	v_mul_f32_e32 v8, v15, v11
	v_mul_f32_e32 v9, 0xbfb8aa3b, v12
	v_mul_f32_e32 v11, 0xbfb8aa3b, v13
	v_exp_f32_e32 v9, v9
	v_exp_f32_e32 v14, v11
	v_mul_f32_e32 v5, v5, v22
	v_mul_f32_e32 v8, v8, v23
	v_add_f32_e32 v9, 1.0, v9
	v_add_f32_e32 v14, 1.0, v14
	v_rcp_f32_e32 v9, v9
	v_rcp_f32_e32 v14, v14
	v_mov_b32_e32 v11, v171
	v_cvt_pk_fp8_f32 v11, v5, v8
	v_mul_f32_e32 v20, s12, v116
	v_mul_f32_e32 v21, s12, v117
	v_mul_f32_e32 v5, v12, v9
	v_mul_f32_e32 v8, v13, v14
	v_mul_f32_e32 v5, v5, v20
	v_mul_f32_e32 v8, v8, v21
	v_cvt_pk_fp8_f32 v11, v5, v8 op_sel:[0,0,1]
	v_mul_f32_e32 v8, s12, v110
	v_mul_f32_e32 v9, s12, v111
	v_or_b32_e32 v6, 32, v4
	v_mul_f32_e32 v18, 0xbfb8aa3b, v8
	v_exp_f32_e32 v20, v18
	v_mul_f32_e32 v18, 0xbfb8aa3b, v9
	v_exp_f32_e32 v21, v18
	v_ashrrev_i32_e32 v7, 31, v6
	v_add_f32_e32 v20, 1.0, v20
	v_rcp_f32_e32 v22, v20
	v_add_f32_e32 v20, 1.0, v21
	v_lshlrev_b64 v[6:7], 7, v[6:7]
	v_rcp_f32_e32 v23, v20
	v_lshl_add_u64 v[6:7], s[4:5], 0, v[6:7]
	v_lshl_add_u64 v[6:7], v[6:7], 0, s[2:3]
	v_lshl_add_u64 v[6:7], v[6:7], 0, v[170:171]
	v_mul_f32_e32 v16, s12, v102
	v_mul_f32_e32 v17, s12, v103
	v_mul_f32_e32 v8, v8, v22
	global_store_dwordx2 v[6:7], v[10:11], off
	v_mul_f32_e32 v6, s12, v112
	v_mul_f32_e32 v7, s12, v113
	v_mul_f32_e32 v16, v8, v16
	v_mul_f32_e32 v8, v9, v23
	v_mul_f32_e32 v9, v8, v17
	v_mul_f32_e32 v8, 0xbfb8aa3b, v6
	v_exp_f32_e32 v17, v8
	v_mul_f32_e32 v8, 0xbfb8aa3b, v7
	v_mul_f32_e32 v12, s12, v106
	v_mul_f32_e32 v13, s12, v107
	v_exp_f32_e32 v22, v8
	v_add_f32_e32 v17, 1.0, v17
	v_rcp_f32_e32 v17, v17
	v_mov_b32_e32 v8, v171
	v_cvt_pk_fp8_f32 v8, v16, v9
	v_mul_f32_e32 v9, 0xbfb8aa3b, v12
	v_mul_f32_e32 v14, s12, v104
	v_mul_f32_e32 v15, s12, v105
	v_mul_f32_e32 v6, v6, v17
	v_exp_f32_e32 v9, v9
	v_mul_f32_e32 v6, v6, v14
	v_mul_f32_e32 v14, 0xbfb8aa3b, v13
	v_add_f32_e32 v22, 1.0, v22
	v_exp_f32_e32 v14, v14
	v_rcp_f32_e32 v22, v22
	v_add_f32_e32 v9, 1.0, v9
	v_rcp_f32_e32 v9, v9
	v_add_f32_e32 v14, 1.0, v14
	v_mul_f32_e32 v7, v7, v22
	v_rcp_f32_e32 v14, v14
	v_mul_f32_e32 v10, s12, v108
	v_mul_f32_e32 v11, s12, v109
	v_mul_f32_e32 v7, v7, v15
	v_cvt_pk_fp8_f32 v8, v6, v7 op_sel:[0,0,1]
	v_mul_f32_e32 v6, v12, v9
	v_mul_f32_e32 v9, 0xbfb8aa3b, v10
	v_exp_f32_e32 v12, v9
	v_mul_f32_e32 v9, 0xbfb8aa3b, v11
	v_mul_f32_e32 v7, v13, v14
	v_exp_f32_e32 v13, v9
	v_add_f32_e32 v12, 1.0, v12
	v_mul_f32_e32 v20, s12, v98
	v_mul_f32_e32 v21, s12, v99
	v_rcp_f32_e32 v12, v12
	v_add_f32_e32 v13, 1.0, v13
	v_rcp_f32_e32 v13, v13
	v_mul_f32_e32 v6, v6, v20
	v_mul_f32_e32 v7, v7, v21
	v_mov_b32_e32 v9, v171
	v_cvt_pk_fp8_f32 v9, v6, v7
	v_or_b32_e32 v4, 48, v4
	v_mul_f32_e32 v18, s12, v100
	v_mul_f32_e32 v19, s12, v101
	v_mul_f32_e32 v6, v10, v12
	v_mul_f32_e32 v7, v11, v13
	v_ashrrev_i32_e32 v5, 31, v4
	v_mul_f32_e32 v6, v6, v18
	v_mul_f32_e32 v7, v7, v19
	v_cvt_pk_fp8_f32 v9, v6, v7 op_sel:[0,0,1]
	v_lshlrev_b64 v[4:5], 7, v[4:5]
	v_lshl_add_u64 v[4:5], s[4:5], 0, v[4:5]
	v_lshl_add_u64 v[4:5], v[4:5], 0, s[2:3]
	v_lshl_add_u64 v[4:5], v[4:5], 0, v[170:171]
	global_store_dwordx2 v[4:5], v[8:9], off
	v_mul_f32_e32 v4, s12, v94
	v_mul_f32_e32 v5, s12, v95
	v_mul_f32_e32 v14, s12, v86
	v_mul_f32_e32 v15, s12, v87
	v_mul_f32_e32 v16, 0xbfb8aa3b, v4
	v_exp_f32_e32 v18, v16
	v_mul_f32_e32 v16, 0xbfb8aa3b, v5
	v_exp_f32_e32 v19, v16
	v_pk_mul_f32 v[6:7], v[96:97], s[12:13] op_sel_hi:[1,0]
	v_add_f32_e32 v18, 1.0, v18
	v_rcp_f32_e32 v20, v18
	v_add_f32_e32 v18, 1.0, v19
	v_rcp_f32_e32 v21, v18
	v_pk_mul_f32 v[10:11], v[90:91], s[12:13] op_sel_hi:[1,0]
	v_mul_f32_e32 v4, v4, v20
	v_mul_f32_e32 v14, v4, v14
	v_mul_f32_e32 v4, v5, v21
	v_mul_f32_e32 v5, v4, v15
	v_mul_f32_e32 v4, 0xbfb8aa3b, v6
	v_exp_f32_e32 v15, v4
	v_mul_f32_e32 v4, 0xbfb8aa3b, v7
	v_exp_f32_e32 v20, v4
	v_mov_b32_e32 v4, v171
	v_add_f32_e32 v15, 1.0, v15
	v_rcp_f32_e32 v15, v15
	v_add_f32_e32 v20, 1.0, v20
	v_rcp_f32_e32 v20, v20
	v_pk_mul_f32 v[12:13], v[88:89], s[12:13] op_sel_hi:[1,0]
	v_cvt_pk_fp8_f32 v4, v14, v5
	v_mul_f32_e32 v5, v6, v15
	v_mul_f32_e32 v6, v7, v20
	v_mul_f32_e32 v7, 0xbfb8aa3b, v10
	v_mul_f32_e32 v5, v5, v12
	v_exp_f32_e32 v7, v7
	v_mul_f32_e32 v12, 0xbfb8aa3b, v11
	v_exp_f32_e32 v12, v12
	v_mul_f32_e32 v6, v6, v13
	v_add_f32_e32 v7, 1.0, v7
	v_rcp_f32_e32 v7, v7
	v_add_f32_e32 v12, 1.0, v12
	v_rcp_f32_e32 v12, v12
	v_pk_mul_f32 v[18:19], v[82:83], s[12:13] op_sel_hi:[1,0]
	v_cvt_pk_fp8_f32 v4, v5, v6 op_sel:[0,0,1]
	v_mul_f32_e32 v5, v10, v7
	v_pk_mul_f32 v[8:9], v[92:93], s[12:13] op_sel_hi:[1,0]
	v_mul_f32_e32 v6, v5, v18
	v_mul_f32_e32 v5, v11, v12
	v_mul_f32_e32 v7, v5, v19
	v_mul_f32_e32 v5, 0xbfb8aa3b, v8
	v_exp_f32_e32 v10, v5
	v_mul_f32_e32 v5, 0xbfb8aa3b, v9
	v_exp_f32_e32 v11, v5
	v_mov_b32_e32 v5, v171
	v_add_f32_e32 v10, 1.0, v10
	v_rcp_f32_e32 v10, v10
	v_add_f32_e32 v11, 1.0, v11
	v_rcp_f32_e32 v11, v11
	v_cvt_pk_fp8_f32 v5, v6, v7
	v_mul_f32_e32 v6, v8, v10
	v_pk_mul_f32 v[18:19], v[70:71], s[12:13] op_sel_hi:[1,0]
	v_mul_f32_e32 v7, v9, v11
	v_pk_mul_f32 v[10:11], v[78:79], s[12:13] op_sel_hi:[1,0]
	v_pk_mul_f32 v[8:9], v[80:81], s[12:13] op_sel_hi:[1,0]
	v_mul_f32_e32 v20, 0xbfb8aa3b, v10
	v_exp_f32_e32 v22, v20
	v_mul_f32_e32 v20, 0xbfb8aa3b, v11
	v_exp_f32_e32 v23, v20
	v_pk_mul_f32 v[14:15], v[74:75], s[12:13] op_sel_hi:[1,0]
	v_add_f32_e32 v22, 1.0, v22
	v_rcp_f32_e32 v24, v22
	v_add_f32_e32 v22, 1.0, v23
	v_rcp_f32_e32 v25, v22
	v_pk_mul_f32 v[16:17], v[84:85], s[12:13] op_sel_hi:[1,0]
	v_mul_f32_e32 v10, v10, v24
	v_mul_f32_e32 v18, v10, v18
	v_mul_f32_e32 v10, v11, v25
	v_mul_f32_e32 v11, v10, v19
	v_mul_f32_e32 v10, 0xbfb8aa3b, v8
	v_exp_f32_e32 v19, v10
	v_mul_f32_e32 v10, 0xbfb8aa3b, v9
	v_exp_f32_e32 v24, v10
	v_mov_b32_e32 v10, v171
	v_add_f32_e32 v19, 1.0, v19
	v_rcp_f32_e32 v19, v19
	v_cvt_pk_fp8_f32 v10, v18, v11
	v_mul_f32_e32 v11, 0xbfb8aa3b, v14
	v_mul_f32_e32 v6, v6, v16
	v_mul_f32_e32 v7, v7, v17
	v_pk_mul_f32 v[16:17], v[72:73], s[12:13] op_sel_hi:[1,0]
	v_mul_f32_e32 v8, v8, v19
	v_exp_f32_e32 v11, v11
	v_mul_f32_e32 v8, v8, v16
	v_mul_f32_e32 v16, 0xbfb8aa3b, v15
	v_add_f32_e32 v24, 1.0, v24
	v_exp_f32_e32 v16, v16
	v_rcp_f32_e32 v24, v24
	v_add_f32_e32 v11, 1.0, v11
	v_rcp_f32_e32 v11, v11
	v_add_f32_e32 v16, 1.0, v16
	v_mul_f32_e32 v9, v9, v24
	v_rcp_f32_e32 v16, v16
	v_pk_mul_f32 v[12:13], v[76:77], s[12:13] op_sel_hi:[1,0]
	v_mul_f32_e32 v9, v9, v17
	v_cvt_pk_fp8_f32 v10, v8, v9 op_sel:[0,0,1]
	v_mul_f32_e32 v8, v14, v11
	v_mul_f32_e32 v11, 0xbfb8aa3b, v12
	v_exp_f32_e32 v14, v11
	v_mul_f32_e32 v11, 0xbfb8aa3b, v13
	v_mul_f32_e32 v9, v15, v16
	v_exp_f32_e32 v15, v11
	v_add_f32_e32 v14, 1.0, v14
	v_rcp_f32_e32 v14, v14
	v_pk_mul_f32 v[22:23], v[66:67], s[12:13] op_sel_hi:[1,0]
	v_add_f32_e32 v15, 1.0, v15
	v_rcp_f32_e32 v15, v15
	v_mul_f32_e32 v8, v8, v22
	v_mul_f32_e32 v9, v9, v23
	v_mov_b32_e32 v11, v171
	v_cvt_pk_fp8_f32 v11, v8, v9
	v_mul_f32_e32 v8, v12, v14
	v_mul_f32_e32 v9, v13, v15
	v_pk_mul_f32 v[12:13], v[62:63], s[12:13] op_sel_hi:[1,0]
	v_pk_mul_f32 v[20:21], v[68:69], s[12:13] op_sel_hi:[1,0]
	v_mul_f32_e32 v22, 0xbfb8aa3b, v12
	v_exp_f32_e32 v24, v22
	v_mul_f32_e32 v22, 0xbfb8aa3b, v13
	v_exp_f32_e32 v25, v22
	v_mul_f32_e32 v8, v8, v20
	v_add_f32_e32 v24, 1.0, v24
	v_rcp_f32_e32 v26, v24
	v_add_f32_e32 v24, 1.0, v25
	v_rcp_f32_e32 v27, v24
	v_mul_f32_e32 v9, v9, v21
	v_pk_mul_f32 v[20:21], v[54:55], s[12:13] op_sel_hi:[1,0]
	v_mul_f32_e32 v12, v12, v26
	v_cvt_pk_fp8_f32 v11, v8, v9 op_sel:[0,0,1]
	v_pk_mul_f32 v[8:9], v[64:65], s[12:13] op_sel_hi:[1,0]
	v_mul_f32_e32 v20, v12, v20
	v_mul_f32_e32 v12, v13, v27
	v_mul_f32_e32 v13, v12, v21
	v_mul_f32_e32 v12, 0xbfb8aa3b, v8
	v_exp_f32_e32 v21, v12
	v_mul_f32_e32 v12, 0xbfb8aa3b, v9
	v_pk_mul_f32 v[16:17], v[58:59], s[12:13] op_sel_hi:[1,0]
	v_exp_f32_e32 v26, v12
	v_add_f32_e32 v21, 1.0, v21
	v_rcp_f32_e32 v21, v21
	v_mov_b32_e32 v12, v171
	v_cvt_pk_fp8_f32 v12, v20, v13
	v_mul_f32_e32 v13, 0xbfb8aa3b, v16
	v_pk_mul_f32 v[18:19], v[56:57], s[12:13] op_sel_hi:[1,0]
	v_mul_f32_e32 v8, v8, v21
	v_exp_f32_e32 v13, v13
	v_mul_f32_e32 v8, v8, v18
	v_mul_f32_e32 v18, 0xbfb8aa3b, v17
	v_add_f32_e32 v26, 1.0, v26
	v_exp_f32_e32 v18, v18
	v_rcp_f32_e32 v26, v26
	v_add_f32_e32 v13, 1.0, v13
	v_rcp_f32_e32 v13, v13
	v_add_f32_e32 v18, 1.0, v18
	v_mul_f32_e32 v9, v9, v26
	v_rcp_f32_e32 v18, v18
	v_pk_mul_f32 v[14:15], v[60:61], s[12:13] op_sel_hi:[1,0]
	v_mul_f32_e32 v9, v9, v19
	v_cvt_pk_fp8_f32 v12, v8, v9 op_sel:[0,0,1]
	v_mul_f32_e32 v8, v16, v13
	v_mul_f32_e32 v13, 0xbfb8aa3b, v14
	v_exp_f32_e32 v16, v13
	v_mul_f32_e32 v13, 0xbfb8aa3b, v15
	v_mul_f32_e32 v9, v17, v18
	v_exp_f32_e32 v17, v13
	v_add_f32_e32 v16, 1.0, v16
	v_rcp_f32_e32 v16, v16
	v_pk_mul_f32 v[24:25], v[50:51], s[12:13] op_sel_hi:[1,0]
	v_add_f32_e32 v17, 1.0, v17
	v_rcp_f32_e32 v17, v17
	v_mul_f32_e32 v8, v8, v24
	v_mul_f32_e32 v9, v9, v25
	v_mov_b32_e32 v13, v171
	v_cvt_pk_fp8_f32 v13, v8, v9
	v_mul_f32_e32 v8, v14, v16
	v_mul_f32_e32 v9, v15, v17
	v_pk_mul_f32 v[14:15], v[46:47], s[12:13] op_sel_hi:[1,0]
	v_pk_mul_f32 v[22:23], v[52:53], s[12:13] op_sel_hi:[1,0]
	v_mul_f32_e32 v24, 0xbfb8aa3b, v14
	v_exp_f32_e32 v26, v24
	v_mul_f32_e32 v24, 0xbfb8aa3b, v15
	v_exp_f32_e32 v27, v24
	v_mul_f32_e32 v8, v8, v22
	v_add_f32_e32 v26, 1.0, v26
	v_rcp_f32_e32 v28, v26
	v_add_f32_e32 v26, 1.0, v27
	v_rcp_f32_e32 v29, v26
	v_mul_f32_e32 v9, v9, v23
	v_pk_mul_f32 v[22:23], v[38:39], s[12:13] op_sel_hi:[1,0]
	v_mul_f32_e32 v14, v14, v28
	v_cvt_pk_fp8_f32 v13, v8, v9 op_sel:[0,0,1]
	v_pk_mul_f32 v[8:9], v[48:49], s[12:13] op_sel_hi:[1,0]
	v_mul_f32_e32 v22, v14, v22
	v_mul_f32_e32 v14, v15, v29
	v_mul_f32_e32 v15, v14, v23
	v_mul_f32_e32 v14, 0xbfb8aa3b, v8
	v_exp_f32_e32 v23, v14
	v_mul_f32_e32 v14, 0xbfb8aa3b, v9
	v_pk_mul_f32 v[18:19], v[42:43], s[12:13] op_sel_hi:[1,0]
	v_exp_f32_e32 v28, v14
	v_add_f32_e32 v23, 1.0, v23
	v_rcp_f32_e32 v23, v23
	v_mov_b32_e32 v14, v171
	v_cvt_pk_fp8_f32 v14, v22, v15
	v_mul_f32_e32 v15, 0xbfb8aa3b, v18
	v_pk_mul_f32 v[20:21], v[40:41], s[12:13] op_sel_hi:[1,0]
	v_mul_f32_e32 v8, v8, v23
	v_exp_f32_e32 v15, v15
	v_mul_f32_e32 v8, v8, v20
	v_mul_f32_e32 v20, 0xbfb8aa3b, v19
	v_add_f32_e32 v28, 1.0, v28
	v_exp_f32_e32 v20, v20
	v_rcp_f32_e32 v28, v28
	v_add_f32_e32 v15, 1.0, v15
	v_rcp_f32_e32 v15, v15
	v_add_f32_e32 v20, 1.0, v20
	v_mul_f32_e32 v9, v9, v28
	v_rcp_f32_e32 v20, v20
	v_pk_mul_f32 v[16:17], v[44:45], s[12:13] op_sel_hi:[1,0]
	v_mul_f32_e32 v9, v9, v21
	v_cvt_pk_fp8_f32 v14, v8, v9 op_sel:[0,0,1]
	v_mul_f32_e32 v8, v18, v15
	v_mul_f32_e32 v15, 0xbfb8aa3b, v16
	v_exp_f32_e32 v18, v15
	v_mul_f32_e32 v15, 0xbfb8aa3b, v17
	v_mul_f32_e32 v9, v19, v20
	v_exp_f32_e32 v19, v15
	v_add_f32_e32 v18, 1.0, v18
	v_pk_mul_f32 v[26:27], v[34:35], s[12:13] op_sel_hi:[1,0]
	v_rcp_f32_e32 v18, v18
	v_add_f32_e32 v19, 1.0, v19
	v_rcp_f32_e32 v19, v19
	v_mul_f32_e32 v8, v8, v26
	v_mul_f32_e32 v9, v9, v27
	v_mov_b32_e32 v15, v171
	v_cvt_pk_fp8_f32 v5, v6, v7 op_sel:[0,0,1]
	v_add_co_u32_e32 v6, vcc, s38, v2
	v_cvt_pk_fp8_f32 v15, v8, v9
	s_nop 0
	v_addc_co_u32_e32 v7, vcc, 0, v3, vcc
	v_add_co_u32_e32 v2, vcc, s44, v2
	v_pk_mul_f32 v[24:25], v[36:37], s[12:13] op_sel_hi:[1,0]
	v_mul_f32_e32 v8, v16, v18
	v_mul_f32_e32 v9, v17, v19
	v_addc_co_u32_e32 v3, vcc, 0, v3, vcc
	v_mul_f32_e32 v8, v8, v24
	v_mul_f32_e32 v9, v9, v25
	v_cvt_pk_fp8_f32 v15, v8, v9 op_sel:[0,0,1]
	s_andn2_b64 vcc, exec, s[10:11]
	s_mov_b64 s[4:5], -1
	global_store_dwordx2 v[2:3], v[4:5], off offset:-4096
	global_store_dwordx2 v[6:7], v[10:11], off offset:2048
	global_store_dwordx2 v[2:3], v[12:13], off
	global_store_dwordx2 v[2:3], v[14:15], off offset:2048
	s_cbranch_vccnz .LBB0_2476
	s_andn2_b64 vcc, exec, s[6:7]
	s_cbranch_vccnz .LBB0_2475
	s_barrier
	s_branch .LBB0_2475

.LBB0_2717:
	s_lshl_b32 s4, s4, 8
	v_mov_b32_e32 v2, v178
	s_add_i32 s4, s4, s34
	s_nop 15
	s_nop 15
	v_readlane_b32 s22, v245, 27
	v_and_or_b32 v4, v2, 15, s4
	s_lshl_b32 s4, s2, 8
	v_bfe_u32 v5, v2, 4, 2
	s_or_b32 s4, s4, s35
	v_lshl_or_b32 v2, v5, 3, s4
	v_cmp_eq_u32_e32 vcc, 0, v5
	v_ashrrev_i32_e32 v5, 31, v4
	v_lshlrev_b64 v[6:7], 13, v[4:5]
	v_readlane_b32 s23, v245, 28
	v_ashrrev_i32_e32 v3, 31, v2
	v_mul_f32_e32 v8, s12, v160
	v_mul_f32_e32 v9, s12, v161
	v_lshl_add_u64 v[6:7], s[22:23], 0, v[6:7]
	v_lshl_add_u64 v[12:13], v[2:3], 1, v[6:7]
	v_mul_f32_e32 v6, s12, v158
	v_mul_f32_e32 v7, s12, v159
	v_mul_f32_e32 v17, v9, v9
	v_mul_f32_e32 v16, v7, v7
	v_mul_f32_e32 v10, s12, v156
	v_mul_f32_e32 v11, s12, v157
	v_mul_f32_e32 v14, s12, v154
	v_mul_f32_e32 v15, s12, v155
	v_fmac_f32_e32 v16, v6, v6
	v_fmac_f32_e32 v17, v8, v8
	v_add_f32_e32 v16, v16, v17
	v_mul_f32_e32 v17, v15, v15
	v_mul_f32_e32 v18, v11, v11
	v_fmac_f32_e32 v17, v14, v14
	v_fmac_f32_e32 v18, v10, v10
	v_add_f32_e32 v17, v17, v18
	v_add_f32_e32 v24, v16, v17
	v_mul_f32_e32 v16, s12, v152
	v_mul_f32_e32 v17, s12, v153
	v_mul_f32_e32 v18, s12, v150
	v_mul_f32_e32 v19, s12, v151
	v_cvt_pk_bf16_f32 v6, v6, v7
	v_cvt_pk_bf16_f32 v7, v8, v9
	v_mul_f32_e32 v9, v17, v17
	v_mul_f32_e32 v8, v19, v19
	v_mul_f32_e32 v20, s12, v148
	v_mul_f32_e32 v21, s12, v149
	v_mul_f32_e32 v22, s12, v146
	v_mul_f32_e32 v23, s12, v147
	v_fmac_f32_e32 v8, v18, v18
	v_fmac_f32_e32 v9, v16, v16
	v_add_f32_e32 v8, v8, v9
	v_mul_f32_e32 v9, v23, v23
	v_mul_f32_e32 v25, v21, v21
	v_fmac_f32_e32 v9, v22, v22
	v_fmac_f32_e32 v25, v20, v20
	v_add_f32_e32 v9, v9, v25
	v_add_f32_e32 v8, v8, v9
	v_add_f32_e32 v24, v24, v8
	ds_bpermute_b32 v25, v218, v24
	v_cvt_pk_bf16_f32 v8, v14, v15
	v_cvt_pk_bf16_f32 v9, v10, v11
	global_store_dwordx4 v[12:13], v[6:9], off
	s_lshl_b32 s4, s2, 2
	s_ashr_i32 s5, s4, 31
	s_waitcnt lgkmcnt(0)
	v_add_f32_e32 v6, v24, v25
	ds_bpermute_b32 v7, v219, v6
	v_cvt_pk_bf16_f32 v8, v18, v19
	v_cvt_pk_bf16_f32 v9, v16, v17
	v_cvt_pk_bf16_f32 v10, v22, v23
	v_cvt_pk_bf16_f32 v11, v20, v21
	global_store_dwordx4 v[12:13], v[8:11], off offset:256
	s_and_saveexec_b64 s[22:23], vcc
	s_cbranch_execz .LBB0_2719
	v_readlane_b32 s24, v245, 29
	v_lshlrev_b64 v[8:9], 8, v[4:5]
	v_readlane_b32 s25, v245, 30
	s_lshl_b32 s2, s33, 2
	s_waitcnt lgkmcnt(0)
	v_add_f32_e32 v5, v6, v7
	v_lshl_add_u64 v[8:9], s[24:25], 0, v[8:9]
	v_lshl_add_u64 v[8:9], s[4:5], 2, v[8:9]
	v_lshl_add_u64 v[8:9], v[8:9], 0, s[2:3]
	global_store_dword v[8:9], v5, off
.LBB0_2719:
	s_or_b64 exec, exec, s[22:23]
	v_or_b32_e32 v6, 16, v4
	s_waitcnt lgkmcnt(0)
	v_ashrrev_i32_e32 v7, 31, v6
	v_readlane_b32 s22, v245, 27
	v_lshlrev_b64 v[8:9], 13, v[6:7]
	v_readlane_b32 s23, v245, 28
	v_mul_f32_e32 v10, s12, v144
	v_mul_f32_e32 v11, s12, v145
	v_mul_f32_e32 v12, s12, v140
	v_mul_f32_e32 v13, s12, v141
	v_lshl_add_u64 v[8:9], s[22:23], 0, v[8:9]
	v_lshl_add_u64 v[14:15], v[2:3], 1, v[8:9]
	v_mul_f32_e32 v8, s12, v142
	v_mul_f32_e32 v9, s12, v143
	v_mul_f32_e32 v18, v11, v11
	v_mul_f32_e32 v5, v9, v9
	v_mul_f32_e32 v16, s12, v138
	v_mul_f32_e32 v17, s12, v139
	v_fmac_f32_e32 v5, v8, v8
	v_fmac_f32_e32 v18, v10, v10
	v_add_f32_e32 v5, v5, v18
	v_mul_f32_e32 v18, v17, v17
	v_mul_f32_e32 v19, v13, v13
	v_fmac_f32_e32 v18, v16, v16
	v_fmac_f32_e32 v19, v12, v12
	v_add_f32_e32 v18, v18, v19
	v_add_f32_e32 v5, v5, v18
	v_mul_f32_e32 v18, s12, v136
	v_mul_f32_e32 v19, s12, v137
	v_mul_f32_e32 v20, s12, v134
	v_mul_f32_e32 v21, s12, v135
	v_cvt_pk_bf16_f32 v8, v8, v9
	v_cvt_pk_bf16_f32 v9, v10, v11
	v_mul_f32_e32 v11, v19, v19
	v_mul_f32_e32 v10, v21, v21
	v_mul_f32_e32 v22, s12, v132
	v_mul_f32_e32 v23, s12, v133
	v_mul_f32_e32 v24, s12, v130
	v_mul_f32_e32 v25, s12, v131
	v_fmac_f32_e32 v10, v20, v20
	v_fmac_f32_e32 v11, v18, v18
	v_add_f32_e32 v10, v10, v11
	v_mul_f32_e32 v11, v25, v25
	v_mul_f32_e32 v26, v23, v23
	v_fmac_f32_e32 v11, v24, v24
	v_fmac_f32_e32 v26, v22, v22
	v_add_f32_e32 v11, v11, v26
	v_add_f32_e32 v10, v10, v11
	v_add_f32_e32 v5, v5, v10
	ds_bpermute_b32 v26, v218, v5
	v_cvt_pk_bf16_f32 v10, v16, v17
	v_cvt_pk_bf16_f32 v11, v12, v13
	global_store_dwordx4 v[14:15], v[8:11], off
	s_waitcnt lgkmcnt(0)
	v_add_f32_e32 v5, v5, v26
	ds_bpermute_b32 v8, v219, v5
	v_cvt_pk_bf16_f32 v10, v20, v21
	v_cvt_pk_bf16_f32 v11, v18, v19
	v_cvt_pk_bf16_f32 v12, v24, v25
	v_cvt_pk_bf16_f32 v13, v22, v23
	global_store_dwordx4 v[14:15], v[10:13], off offset:256
	s_and_saveexec_b64 s[22:23], vcc
	s_cbranch_execz .LBB0_2721
	v_readlane_b32 s24, v245, 29
	v_lshlrev_b64 v[6:7], 8, v[6:7]
	v_readlane_b32 s25, v245, 30
	s_lshl_b32 s2, s33, 2
	s_waitcnt lgkmcnt(0)
	v_add_f32_e32 v5, v5, v8
	v_lshl_add_u64 v[6:7], s[24:25], 0, v[6:7]
	v_lshl_add_u64 v[6:7], s[4:5], 2, v[6:7]
	v_lshl_add_u64 v[6:7], v[6:7], 0, s[2:3]
	global_store_dword v[6:7], v5, off
.LBB0_2721:
	s_or_b64 exec, exec, s[22:23]
	v_or_b32_e32 v6, 32, v4
	v_ashrrev_i32_e32 v7, 31, v6
	v_readlane_b32 s22, v245, 27
	s_waitcnt lgkmcnt(0)
	v_lshlrev_b64 v[8:9], 13, v[6:7]
	v_readlane_b32 s23, v245, 28
	v_mul_f32_e32 v10, s12, v128
	v_mul_f32_e32 v11, s12, v129
	v_mul_f32_e32 v12, s12, v124
	v_mul_f32_e32 v13, s12, v125
	v_lshl_add_u64 v[8:9], s[22:23], 0, v[8:9]
	v_lshl_add_u64 v[14:15], v[2:3], 1, v[8:9]
	v_mul_f32_e32 v8, s12, v126
	v_mul_f32_e32 v9, s12, v127
	v_mul_f32_e32 v18, v11, v11
	v_mul_f32_e32 v5, v9, v9
	v_mul_f32_e32 v16, s12, v122
	v_mul_f32_e32 v17, s12, v123
	v_fmac_f32_e32 v5, v8, v8
	v_fmac_f32_e32 v18, v10, v10
	v_add_f32_e32 v5, v5, v18
	v_mul_f32_e32 v18, v17, v17
	v_mul_f32_e32 v19, v13, v13
	v_fmac_f32_e32 v18, v16, v16
	v_fmac_f32_e32 v19, v12, v12
	v_add_f32_e32 v18, v18, v19
	v_add_f32_e32 v5, v5, v18
	v_mul_f32_e32 v18, s12, v120
	v_mul_f32_e32 v19, s12, v121
	v_mul_f32_e32 v20, s12, v118
	v_mul_f32_e32 v21, s12, v119
	v_cvt_pk_bf16_f32 v8, v8, v9
	v_cvt_pk_bf16_f32 v9, v10, v11
	v_mul_f32_e32 v11, v19, v19
	v_mul_f32_e32 v10, v21, v21
	v_mul_f32_e32 v22, s12, v116
	v_mul_f32_e32 v23, s12, v117
	v_mul_f32_e32 v24, s12, v114
	v_mul_f32_e32 v25, s12, v115
	v_fmac_f32_e32 v10, v20, v20
	v_fmac_f32_e32 v11, v18, v18
	v_add_f32_e32 v10, v10, v11
	v_mul_f32_e32 v11, v25, v25
	v_mul_f32_e32 v26, v23, v23
	v_fmac_f32_e32 v11, v24, v24
	v_fmac_f32_e32 v26, v22, v22
	v_add_f32_e32 v11, v11, v26
	v_add_f32_e32 v10, v10, v11
	v_add_f32_e32 v5, v5, v10
	ds_bpermute_b32 v26, v218, v5
	v_cvt_pk_bf16_f32 v10, v16, v17
	v_cvt_pk_bf16_f32 v11, v12, v13
	global_store_dwordx4 v[14:15], v[8:11], off
	s_waitcnt lgkmcnt(0)
	v_add_f32_e32 v5, v5, v26
	ds_bpermute_b32 v8, v219, v5
	v_cvt_pk_bf16_f32 v10, v20, v21
	v_cvt_pk_bf16_f32 v11, v18, v19
	v_cvt_pk_bf16_f32 v12, v24, v25
	v_cvt_pk_bf16_f32 v13, v22, v23
	global_store_dwordx4 v[14:15], v[10:13], off offset:256
	s_and_saveexec_b64 s[22:23], vcc
	s_cbranch_execz .LBB0_2723
	v_readlane_b32 s24, v245, 29
	v_lshlrev_b64 v[6:7], 8, v[6:7]
	v_readlane_b32 s25, v245, 30
	s_lshl_b32 s2, s33, 2
	s_waitcnt lgkmcnt(0)
	v_add_f32_e32 v5, v5, v8
	v_lshl_add_u64 v[6:7], s[24:25], 0, v[6:7]
	v_lshl_add_u64 v[6:7], s[4:5], 2, v[6:7]
	v_lshl_add_u64 v[6:7], v[6:7], 0, s[2:3]
	global_store_dword v[6:7], v5, off
.LBB0_2723:
	s_or_b64 exec, exec, s[22:23]
	v_or_b32_e32 v6, 48, v4
	v_ashrrev_i32_e32 v7, 31, v6
	v_readlane_b32 s22, v245, 27
	s_waitcnt lgkmcnt(0)
	v_lshlrev_b64 v[8:9], 13, v[6:7]
	v_readlane_b32 s23, v245, 28
	v_mul_f32_e32 v10, s12, v112
	v_mul_f32_e32 v11, s12, v113
	v_mul_f32_e32 v12, s12, v108
	v_mul_f32_e32 v13, s12, v109
	v_lshl_add_u64 v[8:9], s[22:23], 0, v[8:9]
	v_lshl_add_u64 v[14:15], v[2:3], 1, v[8:9]
	v_mul_f32_e32 v8, s12, v110
	v_mul_f32_e32 v9, s12, v111
	v_mul_f32_e32 v18, v11, v11
	v_mul_f32_e32 v5, v9, v9
	v_mul_f32_e32 v16, s12, v106
	v_mul_f32_e32 v17, s12, v107
	v_fmac_f32_e32 v5, v8, v8
	v_fmac_f32_e32 v18, v10, v10
	v_add_f32_e32 v5, v5, v18
	v_mul_f32_e32 v18, v17, v17
	v_mul_f32_e32 v19, v13, v13
	v_fmac_f32_e32 v18, v16, v16
	v_fmac_f32_e32 v19, v12, v12
	v_add_f32_e32 v18, v18, v19
	v_add_f32_e32 v5, v5, v18
	v_mul_f32_e32 v18, s12, v104
	v_mul_f32_e32 v19, s12, v105
	v_mul_f32_e32 v20, s12, v102
	v_mul_f32_e32 v21, s12, v103
	v_cvt_pk_bf16_f32 v8, v8, v9
	v_cvt_pk_bf16_f32 v9, v10, v11
	v_mul_f32_e32 v11, v19, v19
	v_mul_f32_e32 v10, v21, v21
	v_mul_f32_e32 v22, s12, v100
	v_mul_f32_e32 v23, s12, v101
	v_mul_f32_e32 v24, s12, v98
	v_mul_f32_e32 v25, s12, v99
	v_fmac_f32_e32 v10, v20, v20
	v_fmac_f32_e32 v11, v18, v18
	v_add_f32_e32 v10, v10, v11
	v_mul_f32_e32 v11, v25, v25
	v_mul_f32_e32 v26, v23, v23
	v_fmac_f32_e32 v11, v24, v24
	v_fmac_f32_e32 v26, v22, v22
	v_add_f32_e32 v11, v11, v26
	v_add_f32_e32 v10, v10, v11
	v_add_f32_e32 v5, v5, v10
	ds_bpermute_b32 v26, v218, v5
	v_cvt_pk_bf16_f32 v10, v16, v17
	v_cvt_pk_bf16_f32 v11, v12, v13
	global_store_dwordx4 v[14:15], v[8:11], off
	s_waitcnt lgkmcnt(0)
	v_add_f32_e32 v5, v5, v26
	ds_bpermute_b32 v8, v219, v5
	v_cvt_pk_bf16_f32 v10, v20, v21
	v_cvt_pk_bf16_f32 v11, v18, v19
	v_cvt_pk_bf16_f32 v12, v24, v25
	v_cvt_pk_bf16_f32 v13, v22, v23
	global_store_dwordx4 v[14:15], v[10:13], off offset:256
	s_and_saveexec_b64 s[22:23], vcc
	s_cbranch_execz .LBB0_2725
	v_readlane_b32 s24, v245, 29
	v_lshlrev_b64 v[6:7], 8, v[6:7]
	v_readlane_b32 s25, v245, 30
	s_lshl_b32 s2, s33, 2
	s_waitcnt lgkmcnt(0)
	v_add_f32_e32 v5, v5, v8
	v_lshl_add_u64 v[6:7], s[24:25], 0, v[6:7]
	v_lshl_add_u64 v[6:7], s[4:5], 2, v[6:7]
	v_lshl_add_u64 v[6:7], v[6:7], 0, s[2:3]
	global_store_dword v[6:7], v5, off
.LBB0_2725:
	s_or_b64 exec, exec, s[22:23]
	v_add_u32_e32 v6, 0x80, v4
	v_ashrrev_i32_e32 v7, 31, v6
	v_readlane_b32 s22, v245, 27
	s_waitcnt lgkmcnt(0)
	v_lshlrev_b64 v[8:9], 13, v[6:7]
	v_readlane_b32 s23, v245, 28
	v_mul_f32_e32 v10, s12, v96
	v_mul_f32_e32 v11, s12, v97
	v_mul_f32_e32 v12, s12, v92
	v_mul_f32_e32 v13, s12, v93
	v_lshl_add_u64 v[8:9], s[22:23], 0, v[8:9]
	v_lshl_add_u64 v[14:15], v[2:3], 1, v[8:9]
	v_mul_f32_e32 v8, s12, v94
	v_mul_f32_e32 v9, s12, v95
	v_mul_f32_e32 v18, v11, v11
	v_mul_f32_e32 v5, v9, v9
	v_mul_f32_e32 v16, s12, v90
	v_mul_f32_e32 v17, s12, v91
	v_fmac_f32_e32 v5, v8, v8
	v_fmac_f32_e32 v18, v10, v10
	v_add_f32_e32 v5, v5, v18
	v_mul_f32_e32 v18, v17, v17
	v_mul_f32_e32 v19, v13, v13
	v_fmac_f32_e32 v18, v16, v16
	v_fmac_f32_e32 v19, v12, v12
	v_add_f32_e32 v18, v18, v19
	v_add_f32_e32 v5, v5, v18
	v_mul_f32_e32 v18, s12, v88
	v_mul_f32_e32 v19, s12, v89
	v_mul_f32_e32 v20, s12, v86
	v_mul_f32_e32 v21, s12, v87
	v_cvt_pk_bf16_f32 v8, v8, v9
	v_cvt_pk_bf16_f32 v9, v10, v11
	v_mul_f32_e32 v11, v19, v19
	v_mul_f32_e32 v10, v21, v21
	v_mul_f32_e32 v22, s12, v84
	v_mul_f32_e32 v23, s12, v85
	v_mul_f32_e32 v24, s12, v82
	v_mul_f32_e32 v25, s12, v83
	v_fmac_f32_e32 v10, v20, v20
	v_fmac_f32_e32 v11, v18, v18
	v_add_f32_e32 v10, v10, v11
	v_mul_f32_e32 v11, v25, v25
	v_mul_f32_e32 v26, v23, v23
	v_fmac_f32_e32 v11, v24, v24
	v_fmac_f32_e32 v26, v22, v22
	v_add_f32_e32 v11, v11, v26
	v_add_f32_e32 v10, v10, v11
	v_add_f32_e32 v5, v5, v10
	ds_bpermute_b32 v26, v218, v5
	v_cvt_pk_bf16_f32 v10, v16, v17
	v_cvt_pk_bf16_f32 v11, v12, v13
	global_store_dwordx4 v[14:15], v[8:11], off
	s_waitcnt lgkmcnt(0)
	v_add_f32_e32 v5, v5, v26
	ds_bpermute_b32 v8, v219, v5
	v_cvt_pk_bf16_f32 v10, v20, v21
	v_cvt_pk_bf16_f32 v11, v18, v19
	v_cvt_pk_bf16_f32 v12, v24, v25
	v_cvt_pk_bf16_f32 v13, v22, v23
	global_store_dwordx4 v[14:15], v[10:13], off offset:256
	s_and_saveexec_b64 s[22:23], vcc
	s_cbranch_execz .LBB0_2727
	v_readlane_b32 s24, v245, 29
	v_lshlrev_b64 v[6:7], 8, v[6:7]
	v_readlane_b32 s25, v245, 30
	s_lshl_b32 s2, s33, 2
	s_waitcnt lgkmcnt(0)
	v_add_f32_e32 v5, v5, v8
	v_lshl_add_u64 v[6:7], s[24:25], 0, v[6:7]
	v_lshl_add_u64 v[6:7], s[4:5], 2, v[6:7]
	v_lshl_add_u64 v[6:7], v[6:7], 0, s[2:3]
	global_store_dword v[6:7], v5, off
.LBB0_2727:
	s_or_b64 exec, exec, s[22:23]
	v_add_u32_e32 v6, 0x90, v4
	v_ashrrev_i32_e32 v7, 31, v6
	v_readlane_b32 s22, v245, 27
	s_waitcnt lgkmcnt(0)
	v_lshlrev_b64 v[8:9], 13, v[6:7]
	v_readlane_b32 s23, v245, 28
	v_mul_f32_e32 v10, s12, v80
	v_mul_f32_e32 v11, s12, v81
	v_mul_f32_e32 v12, s12, v76
	v_mul_f32_e32 v13, s12, v77
	v_lshl_add_u64 v[8:9], s[22:23], 0, v[8:9]
	v_lshl_add_u64 v[14:15], v[2:3], 1, v[8:9]
	v_mul_f32_e32 v8, s12, v78
	v_mul_f32_e32 v9, s12, v79
	v_mul_f32_e32 v18, v11, v11
	v_mul_f32_e32 v5, v9, v9
	v_mul_f32_e32 v16, s12, v74
	v_mul_f32_e32 v17, s12, v75
	v_fmac_f32_e32 v5, v8, v8
	v_fmac_f32_e32 v18, v10, v10
	v_add_f32_e32 v5, v5, v18
	v_mul_f32_e32 v18, v17, v17
	v_mul_f32_e32 v19, v13, v13
	v_fmac_f32_e32 v18, v16, v16
	v_fmac_f32_e32 v19, v12, v12
	v_add_f32_e32 v18, v18, v19
	v_add_f32_e32 v5, v5, v18
	v_mul_f32_e32 v18, s12, v72
	v_mul_f32_e32 v19, s12, v73
	v_mul_f32_e32 v20, s12, v70
	v_mul_f32_e32 v21, s12, v71
	v_cvt_pk_bf16_f32 v8, v8, v9
	v_cvt_pk_bf16_f32 v9, v10, v11
	v_mul_f32_e32 v11, v19, v19
	v_mul_f32_e32 v10, v21, v21
	v_mul_f32_e32 v22, s12, v68
	v_mul_f32_e32 v23, s12, v69
	v_mul_f32_e32 v24, s12, v66
	v_mul_f32_e32 v25, s12, v67
	v_fmac_f32_e32 v10, v20, v20
	v_fmac_f32_e32 v11, v18, v18
	v_add_f32_e32 v10, v10, v11
	v_mul_f32_e32 v11, v25, v25
	v_mul_f32_e32 v26, v23, v23
	v_fmac_f32_e32 v11, v24, v24
	v_fmac_f32_e32 v26, v22, v22
	v_add_f32_e32 v11, v11, v26
	v_add_f32_e32 v10, v10, v11
	v_add_f32_e32 v5, v5, v10
	ds_bpermute_b32 v26, v218, v5
	v_cvt_pk_bf16_f32 v10, v16, v17
	v_cvt_pk_bf16_f32 v11, v12, v13
	global_store_dwordx4 v[14:15], v[8:11], off
	s_waitcnt lgkmcnt(0)
	v_add_f32_e32 v5, v5, v26
	ds_bpermute_b32 v8, v219, v5
	v_cvt_pk_bf16_f32 v10, v20, v21
	v_cvt_pk_bf16_f32 v11, v18, v19
	v_cvt_pk_bf16_f32 v12, v24, v25
	v_cvt_pk_bf16_f32 v13, v22, v23
	global_store_dwordx4 v[14:15], v[10:13], off offset:256
	s_and_saveexec_b64 s[22:23], vcc
	s_cbranch_execz .LBB0_2729
	v_readlane_b32 s24, v245, 29
	v_lshlrev_b64 v[6:7], 8, v[6:7]
	v_readlane_b32 s25, v245, 30
	s_lshl_b32 s2, s33, 2
	s_waitcnt lgkmcnt(0)
	v_add_f32_e32 v5, v5, v8
	v_lshl_add_u64 v[6:7], s[24:25], 0, v[6:7]
	v_lshl_add_u64 v[6:7], s[4:5], 2, v[6:7]
	v_lshl_add_u64 v[6:7], v[6:7], 0, s[2:3]
	global_store_dword v[6:7], v5, off
.LBB0_2729:
	s_or_b64 exec, exec, s[22:23]
	v_add_u32_e32 v6, 0xa0, v4
	v_ashrrev_i32_e32 v7, 31, v6
	v_readlane_b32 s22, v245, 27
	s_waitcnt lgkmcnt(0)
	v_lshlrev_b64 v[8:9], 13, v[6:7]
	v_readlane_b32 s23, v245, 28
	v_mul_f32_e32 v10, s12, v64
	v_mul_f32_e32 v11, s12, v65
	v_mul_f32_e32 v12, s12, v60
	v_mul_f32_e32 v13, s12, v61
	v_lshl_add_u64 v[8:9], s[22:23], 0, v[8:9]
	v_lshl_add_u64 v[14:15], v[2:3], 1, v[8:9]
	v_mul_f32_e32 v8, s12, v62
	v_mul_f32_e32 v9, s12, v63
	v_mul_f32_e32 v18, v11, v11
	v_mul_f32_e32 v5, v9, v9
	v_mul_f32_e32 v16, s12, v58
	v_mul_f32_e32 v17, s12, v59
	v_fmac_f32_e32 v5, v8, v8
	v_fmac_f32_e32 v18, v10, v10
	v_add_f32_e32 v5, v5, v18
	v_mul_f32_e32 v18, v17, v17
	v_mul_f32_e32 v19, v13, v13
	v_fmac_f32_e32 v18, v16, v16
	v_fmac_f32_e32 v19, v12, v12
	v_add_f32_e32 v18, v18, v19
	v_add_f32_e32 v5, v5, v18
	v_mul_f32_e32 v18, s12, v56
	v_mul_f32_e32 v19, s12, v57
	v_mul_f32_e32 v20, s12, v54
	v_mul_f32_e32 v21, s12, v55
	v_cvt_pk_bf16_f32 v8, v8, v9
	v_cvt_pk_bf16_f32 v9, v10, v11
	v_mul_f32_e32 v11, v19, v19
	v_mul_f32_e32 v10, v21, v21
	v_mul_f32_e32 v22, s12, v52
	v_mul_f32_e32 v23, s12, v53
	v_mul_f32_e32 v24, s12, v50
	v_mul_f32_e32 v25, s12, v51
	v_fmac_f32_e32 v10, v20, v20
	v_fmac_f32_e32 v11, v18, v18
	v_add_f32_e32 v10, v10, v11
	v_mul_f32_e32 v11, v25, v25
	v_mul_f32_e32 v26, v23, v23
	v_fmac_f32_e32 v11, v24, v24
	v_fmac_f32_e32 v26, v22, v22
	v_add_f32_e32 v11, v11, v26
	v_add_f32_e32 v10, v10, v11
	v_add_f32_e32 v5, v5, v10
	ds_bpermute_b32 v26, v218, v5
	v_cvt_pk_bf16_f32 v10, v16, v17
	v_cvt_pk_bf16_f32 v11, v12, v13
	global_store_dwordx4 v[14:15], v[8:11], off
	s_waitcnt lgkmcnt(0)
	v_add_f32_e32 v5, v5, v26
	ds_bpermute_b32 v8, v219, v5
	v_cvt_pk_bf16_f32 v10, v20, v21
	v_cvt_pk_bf16_f32 v11, v18, v19
	v_cvt_pk_bf16_f32 v12, v24, v25
	v_cvt_pk_bf16_f32 v13, v22, v23
	global_store_dwordx4 v[14:15], v[10:13], off offset:256
	s_and_saveexec_b64 s[22:23], vcc
	s_cbranch_execz .LBB0_2731
	v_readlane_b32 s24, v245, 29
	v_lshlrev_b64 v[6:7], 8, v[6:7]
	v_readlane_b32 s25, v245, 30
	s_lshl_b32 s2, s33, 2
	s_waitcnt lgkmcnt(0)
	v_add_f32_e32 v5, v5, v8
	v_lshl_add_u64 v[6:7], s[24:25], 0, v[6:7]
	v_lshl_add_u64 v[6:7], s[4:5], 2, v[6:7]
	v_lshl_add_u64 v[6:7], v[6:7], 0, s[2:3]
	global_store_dword v[6:7], v5, off
.LBB0_2731:
	s_or_b64 exec, exec, s[22:23]
	v_add_u32_e32 v4, 0xb0, v4
	v_ashrrev_i32_e32 v5, 31, v4
	v_readlane_b32 s22, v245, 27
	v_lshlrev_b64 v[6:7], 13, v[4:5]
	v_readlane_b32 s23, v245, 28
	v_mul_f32_e32 v12, s12, v44
	v_mul_f32_e32 v13, s12, v45
	s_waitcnt lgkmcnt(0)
	v_mul_f32_e32 v8, s12, v42
	v_mul_f32_e32 v9, s12, v43
	v_lshl_add_u64 v[6:7], s[22:23], 0, v[6:7]
	v_lshl_add_u64 v[10:11], v[2:3], 1, v[6:7]
	v_mul_f32_e32 v2, s12, v48
	v_mul_f32_e32 v3, s12, v49
	v_mul_f32_e32 v6, s12, v46
	v_mul_f32_e32 v7, s12, v47
	v_mul_f32_e32 v15, v3, v3
	v_mul_f32_e32 v14, v7, v7
	v_fmac_f32_e32 v14, v6, v6
	v_fmac_f32_e32 v15, v2, v2
	v_add_f32_e32 v14, v14, v15
	v_mul_f32_e32 v15, v9, v9
	v_mul_f32_e32 v16, v13, v13
	v_fmac_f32_e32 v15, v8, v8
	v_fmac_f32_e32 v16, v12, v12
	v_add_f32_e32 v15, v15, v16
	v_add_f32_e32 v20, v14, v15
	v_cvt_pk_bf16_f32 v6, v6, v7
	v_cvt_pk_bf16_f32 v7, v2, v3
	v_mul_f32_e32 v14, s12, v40
	v_mul_f32_e32 v15, s12, v41
	v_mul_f32_e32 v2, s12, v38
	v_mul_f32_e32 v3, s12, v39
	v_mul_f32_e32 v22, v15, v15
	v_mul_f32_e32 v21, v3, v3
	v_mul_f32_e32 v16, s12, v36
	v_mul_f32_e32 v17, s12, v37
	v_mul_f32_e32 v18, s12, v34
	v_mul_f32_e32 v19, s12, v35
	v_fmac_f32_e32 v21, v2, v2
	v_fmac_f32_e32 v22, v14, v14
	v_add_f32_e32 v21, v21, v22
	v_mul_f32_e32 v22, v19, v19
	v_mul_f32_e32 v23, v17, v17
	v_fmac_f32_e32 v22, v18, v18
	v_fmac_f32_e32 v23, v16, v16
	v_add_f32_e32 v22, v22, v23
	v_add_f32_e32 v21, v21, v22
	v_add_f32_e32 v20, v20, v21
	ds_bpermute_b32 v21, v218, v20
	v_cvt_pk_bf16_f32 v8, v8, v9
	v_cvt_pk_bf16_f32 v9, v12, v13
	global_store_dwordx4 v[10:11], v[6:9], off
	s_nop 1
	v_cvt_pk_bf16_f32 v6, v2, v3
	s_waitcnt lgkmcnt(0)
	v_add_f32_e32 v2, v20, v21
	ds_bpermute_b32 v3, v219, v2
	v_cvt_pk_bf16_f32 v7, v14, v15
	v_cvt_pk_bf16_f32 v8, v18, v19
	v_cvt_pk_bf16_f32 v9, v16, v17
	global_store_dwordx4 v[10:11], v[6:9], off offset:256
	s_and_saveexec_b64 s[22:23], vcc
	s_cbranch_execz .LBB0_2733
	v_readlane_b32 s24, v245, 29
	v_lshlrev_b64 v[4:5], 8, v[4:5]
	v_readlane_b32 s25, v245, 30
	s_lshl_b32 s2, s33, 2
	s_waitcnt lgkmcnt(0)
	v_add_f32_e32 v2, v2, v3
	v_lshl_add_u64 v[4:5], s[24:25], 0, v[4:5]
	v_lshl_add_u64 v[4:5], s[4:5], 2, v[4:5]
	v_lshl_add_u64 v[4:5], v[4:5], 0, s[2:3]
	global_store_dword v[4:5], v2, off
